# DeltaNet scan loop rewritten by hand: u/o wave roles, each fragment loaded once, 4 register sets prefetched 3 steps ahead; HG scan prefetch waits relaxed
# speedup vs baseline: 1.0100x; 1.0100x over previous
; __global__ void __launch_bounds__(NTHR, 2) fwd_megakernel(Params p) {
;     ...
;         const int VG = big ? G - 128 : G, vb = big ? p.bid - 128 : p.bid;
;         if (!big || p.bid < 128) {
;           for (int it = p.bid; it < 128; it += (big ? 128 : G)) {
;             const int item = (it & 7) * 16 + (it >> 3);
;             if (kind == 3) dn_scan_block(p, L, item); else hg_scan_block(p, L, item);
;           }
;         }
;         if ((!big || p.bid >= 128) && rep == 0) {
;           const int cL0 = L, cj0 = (L & 1) ? 2 : 1, cL1 = (L < 3) ? L + 1 : 3, cj1 = (L == 3) ? 4 : ((L & 1) ? 0 : 1);
;           cvt_jobs(p, cL0, cj0, cL1, cj1, vb, VG);
.LBB0_255:
	v_readlane_b32 s0, v254, 55
	v_readlane_b32 s1, v254, 56
	s_cmpk_gt_i32 s0, 0x7f
	v_readlane_b32 s2, v252, 26
	s_cselect_b64 s[0:1], -1, 0
	v_readlane_b32 s3, v252, 27
	s_or_b64 s[0:1], s[2:3], s[0:1]
	s_andn2_b64 vcc, exec, s[0:1]
	s_cbranch_vccnz .LBB0_364
	v_readlane_b32 s0, v254, 55
	v_readlane_b32 s1, v254, 56
	s_mov_b32 s12, s0
	s_add_i32 s2, s0, 0xffffff80
	v_readlane_b32 s0, v252, 26
	v_readlane_b32 s1, v252, 27
	s_and_b64 s[0:1], s[0:1], exec
	v_readlane_b32 s1, v254, 53
	s_cselect_b32 s66, s12, s2
	s_min_u32 s67, s1, 2
	s_add_i32 s74, s67, 1
	v_writelane_b32 v255, s70, 6
	s_cmp_gt_u32 s1, s74
	s_cbranch_scc1 .LBB0_347
	s_add_i32 s2, s68, 1
	s_xor_b32 s0, s68, 1
	s_cmp_lg_u32 s1, 3
	s_cselect_b32 s3, s0, 4
	v_writelane_b32 v254, s2, 58
	s_mov_b32 s24, 0
	s_mov_b32 s73, s1
	v_writelane_b32 v254, s3, 60
	s_branch .LBB0_278
.LBB0_259:
	s_add_i32 s20, s20, s54
	s_cmpk_lt_i32 s20, 0x80
	s_cbranch_scc0 .LBB0_255

; __device__ void hg_scan_block(const Params& p, int L, int item) {
;     ...
;   HG_LOAD(A, 0); HG_LOAD(B, 1);
;   __syncthreads();
.LBB0_264:
	s_or_b64 exec, exec, s[12:13]
	s_ashr_i32 s41, s40, 31
	v_bfe_u32 v104, v0, 4, 2
	s_lshl_b64 s[42:43], s[40:41], 12
	v_or_b32_e32 v2, s42, v104
	v_mov_b64_e32 v[46:47], s[16:17]
	s_lshl_b32 s1, s0, 7
	v_mad_u64_u32 v[2:3], s[2:3], v2, s89, v[46:47]
	v_mov_b32_e32 v57, 0x2400
	s_and_b32 s1, s1, 0x180
	v_readlane_b32 s36, v254, 13
	v_and_b32_e32 v103, 15, v0
	v_mad_i32_i24 v3, s43, v57, v3
	v_readlane_b32 s37, v254, 14
	s_lshl_b32 s36, s1, 1
	v_ashrrev_i32_e32 v102, 6, v0
	v_lshl_add_u64 v[2:3], v[2:3], 0, s[36:37]
	v_lshlrev_b32_e32 v90, 4, v103
	v_mov_b32_e32 v91, v1
	v_ashrrev_i32_e32 v0, 3, v0
	v_lshl_add_u64 v[6:7], v[2:3], 0, v[90:91]
	v_and_b32_e32 v146, -16, v0
	v_mad_i64_i32 v[2:3], s[2:3], v146, s89, v[6:7]
	v_or_b32_e32 v54, 4, v146
	v_or_b32_e32 v55, 8, v146
	v_mad_i64_i32 v[4:5], s[2:3], v54, s89, v[6:7]
	global_load_dwordx4 v[42:45], v[2:3], off offset:3072
	global_load_dwordx4 v[34:37], v[4:5], off offset:3072
	v_mad_i64_i32 v[2:3], s[2:3], v55, s89, v[6:7]
	v_or_b32_e32 v56, 12, v146
	v_lshlrev_b32_e32 v100, 3, v102
	v_mad_i64_i32 v[4:5], s[2:3], v56, s89, v[6:7]
	global_load_dwordx4 v[38:41], v[2:3], off offset:3072
	global_load_dwordx4 v[26:29], v[4:5], off offset:3072
	v_mad_i64_i32 v[2:3], s[2:3], v100, s89, v[6:7]
	s_movk_i32 s19, 0x1000
	v_add_co_u32_e32 v2, vcc, s19, v2
	s_mul_i32 s14, s21, 0x24000
	s_mov_b32 s15, s37
	v_addc_co_u32_e32 v3, vcc, 0, v3, vcc
	v_lshl_add_u64 v[14:15], v[6:7], 0, s[14:15]
	v_add_co_u32_e32 v8, vcc, s19, v14
	s_mov_b32 s28, 0x13000
	s_nop 0
	v_addc_co_u32_e32 v9, vcc, 0, v15, vcc
	v_or_b32_e32 v78, 4, v100
	global_load_dwordx4 v[2:5], v[2:3], off
	s_nop 0
	global_load_dwordx4 v[18:21], v[8:9], off offset:1024
	v_add_co_u32_e32 v8, vcc, s28, v14
	v_mad_i64_i32 v[6:7], s[2:3], v78, s89, v[6:7]
	v_and_b32_e32 v105, 1, v102
	v_addc_co_u32_e32 v9, vcc, 0, v15, vcc
	s_lshl_b32 s2, s21, 5
	v_ashrrev_i32_e32 v147, 31, v146
	v_add_co_u32_e32 v6, vcc, s19, v6
	v_lshl_or_b32 v30, v105, 4, s2
	s_nop 0
	v_addc_co_u32_e32 v7, vcc, 0, v7, vcc
	s_mov_b32 s25, 0xa000
	v_lshl_add_u64 v[92:93], s[42:43], 0, v[146:147]
	v_lshlrev_b32_e32 v0, 2, v104
	v_or3_b32 v148, v30, v103, s1
	v_lshlrev_b32_e32 v30, 4, v102
	v_add_co_u32_e32 v16, vcc, s25, v14
	v_or_b32_e32 v92, v92, v0
	v_ashrrev_i32_e32 v31, 31, v30
	v_addc_co_u32_e32 v17, vcc, 0, v15, vcc
	s_mov_b32 s26, 0x1c000
	v_lshlrev_b64 v[94:95], 2, v[30:31]
	v_mad_u64_u32 v[30:31], s[22:23], v92, s89, v[46:47]
	v_add_co_u32_e32 v14, vcc, s26, v14
	v_mad_i32_i24 v31, v93, s89, v31
	v_lshlrev_b32_e32 v96, 1, v148
	v_mov_b32_e32 v97, v1
	v_addc_co_u32_e32 v15, vcc, 0, v15, vcc
	v_lshl_add_u64 v[30:31], v[30:31], 0, v[96:97]
	v_add_co_u32_e32 v32, vcc, s19, v30
	s_ashr_i32 s1, s0, 31
	s_nop 0
	v_addc_co_u32_e32 v33, vcc, 0, v31, vcc
	v_add_co_u32_e32 v48, vcc, s63, v30
	s_lshl_b64 s[12:13], s[0:1], 15
	s_nop 0
	v_addc_co_u32_e32 v49, vcc, 0, v31, vcc
	s_movk_i32 s1, 0x6000
	global_load_dwordx4 v[10:13], v[8:9], off offset:1024
	s_nop 0
	global_load_dwordx4 v[6:9], v[6:7], off
	s_nop 0
	global_load_dwordx4 v[22:25], v[16:17], off offset:1024
	s_nop 0
	global_load_dwordx4 v[14:17], v[14:15], off offset:1024
	s_nop 0
	global_load_ushort v106, v[32:33], off offset:3072
	global_load_ushort v107, v[48:49], off
	v_add_co_u32_e32 v48, vcc, s1, v30
	s_add_u32 s2, s52, s12
	s_nop 0
	v_addc_co_u32_e32 v49, vcc, 0, v31, vcc
	s_mov_b32 s24, 0x8000
	s_addc_u32 s3, s53, s13
	v_add_co_u32_e32 v30, vcc, s24, v30
	v_lshl_add_u64 v[32:33], s[2:3], 0, v[94:95]
	s_nop 0
	v_addc_co_u32_e32 v31, vcc, 0, v31, vcc
	s_or_b32 s2, s42, 64
	s_mov_b32 s3, s43
	global_load_ushort v108, v[48:49], off offset:1024
	global_load_ushort v109, v[30:31], off offset:2048
	v_lshl_add_u64 v[30:31], s[2:3], 0, v[146:147]
	v_or_b32_e32 v30, v30, v0
	v_mad_u64_u32 v[48:49], s[22:23], v30, s89, v[46:47]
	v_mad_i32_i24 v49, v31, s89, v49
	v_lshl_add_u64 v[30:31], v[48:49], 0, v[96:97]
	v_add_co_u32_e32 v48, vcc, s63, v30
	v_lshlrev_b32_e32 v150, 4, v104
	s_nop 0
	v_addc_co_u32_e32 v49, vcc, 0, v31, vcc
	v_add_co_u32_e32 v50, vcc, s19, v30
	v_mov_b32_e32 v151, v1
	s_nop 0
	v_addc_co_u32_e32 v51, vcc, 0, v31, vcc
	v_add_co_u32_e32 v52, vcc, s24, v30
	v_lshl_add_u64 v[32:33], v[32:33], 0, v[150:151]
	s_nop 0
	v_addc_co_u32_e32 v53, vcc, 0, v31, vcc
	v_add_co_u32_e32 v30, vcc, s1, v30
	s_mov_b32 s1, 0x233000
	s_nop 0
	v_addc_co_u32_e32 v31, vcc, 0, v31, vcc
	global_load_ushort v110, v[48:49], off
	global_load_ushort v111, v[50:51], off offset:3072
	global_load_ushort v112, v[52:53], off offset:2048
	global_load_ushort v113, v[30:31], off offset:1024
	v_or_b32_e32 v48, s2, v104
	v_mad_u64_u32 v[46:47], s[2:3], v48, s89, v[46:47]
	v_mad_i32_i24 v47, s43, v57, v47
	v_lshl_add_u64 v[46:47], v[46:47], 0, s[36:37]
	v_add_co_u32_e32 v74, vcc, s1, v32
	v_lshl_add_u64 v[66:67], v[46:47], 0, v[90:91]
	s_nop 0
	v_addc_co_u32_e32 v75, vcc, 0, v33, vcc
	v_mad_i64_i32 v[58:59], s[2:3], v100, s89, v[66:67]
	v_add_co_u32_e32 v58, vcc, s19, v58
	v_lshl_add_u64 v[76:77], v[66:67], 0, s[14:15]
	s_nop 0
	v_addc_co_u32_e32 v59, vcc, 0, v59, vcc
	v_add_co_u32_e32 v62, vcc, s19, v76
	v_mad_i64_i32 v[46:47], s[2:3], v146, s89, v[66:67]
	s_nop 0
	v_addc_co_u32_e32 v63, vcc, 0, v77, vcc
	v_add_co_u32_e32 v68, vcc, s28, v76
	v_mad_i64_i32 v[48:49], s[2:3], v54, s89, v[66:67]
	v_mad_i64_i32 v[50:51], s[2:3], v55, s89, v[66:67]
	v_mad_i64_i32 v[54:55], s[2:3], v56, s89, v[66:67]
	v_addc_co_u32_e32 v69, vcc, 0, v77, vcc
	v_mad_i64_i32 v[66:67], s[2:3], v78, s89, v[66:67]
	v_add_co_u32_e32 v78, vcc, s19, v66
	global_load_dwordx4 v[30:33], v[74:75], off
	s_nop 0
	v_addc_co_u32_e32 v79, vcc, 0, v67, vcc
; __device__ void hg_scan_block(const Params& p, int L, int item) {
;     ...
;   Sacc[0] = (f32x4){0.f, 0.f, 0.f, 0.f}; Sacc[1] = Sacc[0];
;     ...
;   HG_DECL(A) HG_DECL(B) HG_DECL(C)
;     ...
;   HG_LOAD(A, 0); HG_LOAD(B, 1);
;   __syncthreads();
	global_load_dwordx4 v[70:73], v[46:47], off offset:3072
	s_nop 0
	global_load_dwordx4 v[46:49], v[48:49], off offset:3072
	s_nop 0
	global_load_dwordx4 v[50:53], v[50:51], off offset:3072
	s_nop 0
	global_load_dwordx4 v[54:57], v[54:55], off offset:3072
	s_nop 0
	global_load_dwordx4 v[58:61], v[58:59], off
	s_nop 0
	global_load_dwordx4 v[62:65], v[62:63], off offset:1024
	s_nop 0
	global_load_dwordx4 v[66:69], v[68:69], off offset:1024
	s_nop 0
	global_load_dwordx4 v[82:85], v[78:79], off
	v_add_co_u32_e32 v78, vcc, s25, v76
	s_mov_b32 s1, s37
	s_nop 0
	v_addc_co_u32_e32 v79, vcc, 0, v77, vcc
	v_add_co_u32_e32 v76, vcc, s26, v76
	v_writelane_b32 v254, s0, 13
	s_nop 0
	v_addc_co_u32_e32 v77, vcc, 0, v77, vcc
	global_load_dwordx4 v[86:89], v[78:79], off offset:1024
	s_nop 0
	global_load_dwordx4 v[78:81], v[76:77], off offset:1024
	s_nop 0
	global_load_dwordx4 v[74:77], v[74:75], off offset:512
	v_lshlrev_b32_e32 v179, 5, v102
	v_lshlrev_b32_e32 v180, 3, v104
	v_mad_u32_u24 v91, v103, s88, 0
	v_writelane_b32 v254, s1, 14
	v_add3_u32 v165, v91, v179, v180
	s_mul_hi_i32 s1, s40, 0x2400000
	v_mul_hi_u32_u24_e32 v91, 0x9000, v104
	v_mad_i64_i32 v[98:99], s[2:3], v146, s89, 0
	v_mul_u32_u24_e32 v178, 0x110, v103
	s_mul_i32 s14, s40, 0x2400000
	v_mul_u32_u24_e32 v102, 0x9000, v104
	v_or_b32_e32 v103, s1, v91
	v_mov_b32_e32 v91, 0x2400000
	v_or_b32_e32 v102, s14, v102
	v_mad_i64_i32 v[98:99], s[2:3], s40, v91, v[98:99]
	v_mad_i64_i32 v[100:101], s[2:3], v100, s89, 0
	v_mad_i64_i32 v[102:103], s[2:3], v146, s89, v[102:103]
	v_mad_u64_u32 v[154:155], s[2:3], v104, s89, v[98:99]
	s_lshl_b32 s2, s18, 6
	s_and_b32 s15, s2, 0x300
	v_mad_i64_i32 v[98:99], s[2:3], s40, v91, v[100:101]
	v_mad_u64_u32 v[156:157], s[2:3], v104, s89, v[98:99]
	s_bfe_u32 s2, s20, 0x20003
	s_mul_i32 s2, s2, 0x24000
	s_or_b32 s2, s14, s2
	v_mov_b32_e32 v98, s2
	v_mov_b32_e32 v99, s1
	v_mad_u64_u32 v[158:159], s[2:3], v104, s89, v[98:99]
	s_add_u32 s1, s12, 0x7433608
	s_addc_u32 s2, s13, 0
	v_or3_b32 v154, v154, s15, v90
	v_or3_b32 v156, v156, s15, v90
	v_or3_b32 v158, v158, s15, v90
	v_or_b32_e32 v90, s1, v150
	v_mov_b32_e32 v91, s2
	v_mad_u64_u32 v[162:163], s[2:3], v92, s89, v[96:97]
	v_mov_b32_e32 v138, 0
	s_movk_i32 s28, 0x1000
	s_waitcnt vmcnt(18)
	v_lshlrev_b32_e32 v143, 16, v107
	v_lshlrev_b32_e32 v142, 16, v106
	s_waitcnt vmcnt(16)
	v_lshlrev_b32_e32 v145, 16, v109
	v_lshlrev_b32_e32 v144, 16, v108
	s_waitcnt vmcnt(14)
	v_mov_b32_e32 v149, v111
	v_mov_b32_e32 v164, v110
	s_waitcnt vmcnt(12)
	v_mov_b32_e32 v151, v113
	v_mov_b32_e32 v166, v112
	v_mul_u32_u24_e32 v167, 0x1100, v105
	v_lshl_add_u64 v[152:153], v[102:103], 0, v[96:97]
	v_lshl_add_u64 v[160:161], v[90:91], 0, v[94:95]
	v_mad_i32_i24 v163, v93, s89, v163
	s_mov_b32 s1, -3
	v_mov_b32_e32 v139, v138
	v_mov_b32_e32 v140, v138
	v_mov_b32_e32 v141, v138
	v_mov_b32_e32 v134, v138
	v_mov_b32_e32 v135, v138
	v_mov_b32_e32 v136, v138
	v_mov_b32_e32 v137, v138
	s_waitcnt lgkmcnt(0)
	s_barrier
	s_branch .LBB0_266
.Lhg_scan_last:
	s_waitcnt vmcnt(4)
.LBB0_265:
	ds_read_b128 v[174:177], v185
	ds_read_b128 v[186:189], v185 offset:64
	s_mov_b64 s[2:3], 0xc321c00
	s_waitcnt vmcnt(44)
	v_lshlrev_b32_e32 v170, 16, v184
	s_waitcnt vmcnt(41)
	v_lshlrev_b32_e32 v171, 16, v181
	s_waitcnt vmcnt(39)
	v_lshlrev_b32_e32 v172, 16, v182
	s_waitcnt vmcnt(38)
	v_lshlrev_b32_e32 v173, 16, v183
	v_lshl_add_u64 v[190:191], v[168:169], 0, s[2:3]
	s_mov_b64 s[2:3], 0xc324000
	s_waitcnt lgkmcnt(1)
	v_mfma_f32_16x16x32_bf16 v[102:105], v[102:105], v[174:177], v[170:173]
	v_lshl_add_u64 v[192:193], v[168:169], 0, s[2:3]
	s_mov_b64 s[2:3], 0xc326400
	s_mov_b64 s[14:15], 0x1b0000
	v_lshl_add_u64 v[172:173], v[168:169], 0, s[2:3]
	s_mov_b64 s[2:3], 0xc328800
	v_lshl_add_u64 v[174:175], v[168:169], 0, s[2:3]
	ds_read_b128 v[168:171], v185 offset:128
	s_waitcnt lgkmcnt(1)
	v_mfma_f32_16x16x32_bf16 v[102:105], v[106:109], v[186:189], v[102:105]
	ds_read_b128 v[106:109], v185 offset:192
	s_andn2_b32 s2, 1, s1
	s_mulk_i32 s2, 0x2200
	s_waitcnt lgkmcnt(1)
	v_mfma_f32_16x16x32_bf16 v[102:105], v[118:121], v[168:171], v[102:105]
	s_waitcnt vmcnt(22)
	v_lshlrev_b32_e32 v143, 16, v143
	v_lshlrev_b32_e32 v142, 16, v142
	s_waitcnt vmcnt(19)
	v_lshlrev_b32_e32 v145, 16, v145
	s_waitcnt lgkmcnt(0)
	v_mfma_f32_16x16x32_bf16 v[102:105], v[122:125], v[106:109], v[102:105]
	v_lshlrev_b32_e32 v144, 16, v144
	v_lshl_add_u64 v[152:153], v[152:153], 0, s[14:15]
	v_lshl_add_u64 v[154:155], v[154:155], 0, s[14:15]
	v_lshl_add_u64 v[156:157], v[156:157], 0, s[14:15]
	v_lshl_add_u64 v[158:159], v[158:159], 0, s[14:15]
	s_nop 2
	v_bfe_u32 v106, v102, 16, 1
	v_add3_u32 v102, v102, v106, s72
	global_store_short_d16_hi v[190:191], v102, off
	v_bfe_u32 v102, v103, 16, 1
	v_add3_u32 v102, v103, v102, s72
	global_store_short_d16_hi v[192:193], v102, off
	v_bfe_u32 v102, v104, 16, 1
	v_add3_u32 v102, v104, v102, s72
	global_store_short_d16_hi v[172:173], v102, off
	v_bfe_u32 v102, v105, 16, 1
	v_add3_u32 v106, v105, v102, s72
	v_pk_mul_f32 v[104:105], v[128:129], v[140:141]
	v_pk_mul_f32 v[102:103], v[126:127], v[138:139]
	global_store_short_d16_hi v[174:175], v106, off
	v_add_u32_e32 v106, s2, v165
	v_mfma_f32_16x16x32_bf16 v[102:105], v[90:93], v[110:113], v[102:105]
	s_mov_b64 s[2:3], 0x600
	v_lshl_add_u64 v[160:161], v[160:161], 0, s[2:3]
	s_andn2_b64 vcc, exec, s[12:13]
	v_mfma_f32_16x16x32_bf16 v[138:141], v[98:101], v[130:133], v[102:105]
	v_lshl_add_u64 v[162:163], v[162:163], 0, s[14:15]
	s_nop 2
	v_pk_mul_f32 v[104:105], v[128:129], v[136:137]
	s_nop 2
	v_and_b32_sdwa v102, v140, v220 dst_sel:DWORD dst_unused:UNUSED_PAD src0_sel:WORD_1 src1_sel:DWORD
	v_and_b32_sdwa v103, v138, v220 dst_sel:DWORD dst_unused:UNUSED_PAD src0_sel:WORD_1 src1_sel:DWORD
	v_add3_u32 v107, v138, v103, s72
	v_add3_u32 v108, v140, v102, s72
	v_and_b32_sdwa v102, v141, v220 dst_sel:DWORD dst_unused:UNUSED_PAD src0_sel:WORD_1 src1_sel:DWORD
	v_and_b32_sdwa v103, v139, v220 dst_sel:DWORD dst_unused:UNUSED_PAD src0_sel:WORD_1 src1_sel:DWORD
	v_add3_u32 v102, v141, v102, s72
	v_add3_u32 v103, v139, v103, s72
	v_and_b32_e32 v109, 0xffff0000, v102
	v_and_b32_e32 v110, 0xffff0000, v103
	v_pk_mul_f32 v[102:103], v[126:127], v[134:135]
	s_nop 1
	v_mfma_f32_16x16x32_bf16 v[90:93], v[90:93], v[94:97], v[102:105]
	v_or_b32_sdwa v95, v109, v108 dst_sel:DWORD dst_unused:UNUSED_PAD src0_sel:DWORD src1_sel:WORD_1
	v_or_b32_sdwa v94, v110, v107 dst_sel:DWORD dst_unused:UNUSED_PAD src0_sel:DWORD src1_sel:WORD_1
	ds_write_b64 v106, v[94:95]
	v_mfma_f32_16x16x32_bf16 v[134:137], v[98:101], v[114:117], v[90:93]
	s_nop 7
	v_and_b32_sdwa v91, v134, v220 dst_sel:DWORD dst_unused:UNUSED_PAD src0_sel:WORD_1 src1_sel:DWORD
	v_add3_u32 v92, v134, v91, s72
	v_and_b32_sdwa v91, v137, v220 dst_sel:DWORD dst_unused:UNUSED_PAD src0_sel:WORD_1 src1_sel:DWORD
	v_and_b32_sdwa v93, v135, v220 dst_sel:DWORD dst_unused:UNUSED_PAD src0_sel:WORD_1 src1_sel:DWORD
	v_and_b32_sdwa v90, v136, v220 dst_sel:DWORD dst_unused:UNUSED_PAD src0_sel:WORD_1 src1_sel:DWORD
	v_add3_u32 v91, v137, v91, s72
	v_add3_u32 v93, v135, v93, s72
	v_add3_u32 v90, v136, v90, s72
	v_and_b32_e32 v91, 0xffff0000, v91
	v_and_b32_e32 v93, 0xffff0000, v93
	v_or_b32_sdwa v91, v91, v90 dst_sel:DWORD dst_unused:UNUSED_PAD src0_sel:DWORD src1_sel:WORD_1
	v_or_b32_sdwa v90, v93, v92 dst_sel:DWORD dst_unused:UNUSED_PAD src0_sel:DWORD src1_sel:WORD_1
	ds_write_b64 v106, v[90:91] offset:4352
	s_waitcnt lgkmcnt(0)
	s_barrier
	s_cbranch_vccz .LBB0_269
.LBB0_266:
	v_lshl_add_u64 v[176:177], s[10:11], 0, v[154:155]
	s_mov_b32 s3, 0xc320000
	v_add_co_u32_e32 v90, vcc, s3, v176
	s_mov_b32 s3, 0xc329000
	s_nop 0
	v_addc_co_u32_e32 v91, vcc, 0, v177, vcc
	global_load_dwordx4 v[102:105], v[90:91], off offset:3072
	v_add_co_u32_e32 v90, vcc, s3, v176
	s_mov_b32 s3, 0xc332000
	s_nop 0
	v_addc_co_u32_e32 v91, vcc, 0, v177, vcc
	global_load_dwordx4 v[106:109], v[90:91], off offset:3072
	v_add_co_u32_e32 v90, vcc, s3, v176
	s_mov_b32 s3, 0xc33b000
	s_nop 0
	v_addc_co_u32_e32 v91, vcc, 0, v177, vcc
	global_load_dwordx4 v[118:121], v[90:91], off offset:3072
	v_add_co_u32_e32 v90, vcc, s3, v176
	v_lshl_add_u64 v[172:173], s[10:11], 0, v[156:157]
	s_nop 0
	v_addc_co_u32_e32 v91, vcc, 0, v177, vcc
	s_mov_b32 s12, 0xc321000
	global_load_dwordx4 v[122:125], v[90:91], off offset:3072
	v_add_co_u32_e32 v90, vcc, s12, v172
	v_lshl_add_u64 v[170:171], s[10:11], 0, v[158:159]
	s_nop 0
	v_addc_co_u32_e32 v91, vcc, 0, v173, vcc
	v_add_co_u32_e32 v94, vcc, s12, v170
	s_mov_b32 s3, 0xc333000
	s_nop 0
	v_addc_co_u32_e32 v95, vcc, 0, v171, vcc
	global_load_dwordx4 v[90:93], v[90:91], off
	v_lshl_add_u64 v[168:169], s[10:11], 0, v[152:153]
	global_load_dwordx4 v[110:113], v[94:95], off offset:1024
	v_add_co_u32_e32 v94, vcc, s3, v170
	s_mov_b32 s3, 0xc32a000
	s_nop 0
	v_addc_co_u32_e32 v95, vcc, 0, v171, vcc
	v_add_co_u32_e32 v98, vcc, s3, v172
	s_mov_b32 s2, s1
	s_nop 0
	v_addc_co_u32_e32 v99, vcc, 0, v173, vcc
	v_add_co_u32_e32 v114, vcc, s3, v170
	s_mov_b32 s3, 0xc33c000
	s_nop 0
	v_addc_co_u32_e32 v115, vcc, 0, v171, vcc
	global_load_dwordx4 v[130:133], v[114:115], off offset:1024
	v_add_co_u32_e32 v114, vcc, s3, v170
	s_mov_b32 s3, 0xc324000
	s_nop 0
	v_addc_co_u32_e32 v115, vcc, 0, v171, vcc
	v_add_co_u32_e32 v126, vcc, s12, v168
	global_load_dwordx4 v[114:117], v[114:115], off offset:1024
	s_nop 0
	v_addc_co_u32_e32 v127, vcc, 0, v169, vcc
	global_load_ushort v184, v[126:127], off offset:3072
	v_add_co_u32_e32 v126, vcc, s3, v168
	s_mov_b32 s3, 0xc326000
	s_nop 0
	v_addc_co_u32_e32 v127, vcc, 0, v169, vcc
	s_add_i32 s1, s1, 3
	v_add_co_u32_e32 v182, vcc, s3, v168
	s_mov_b32 s3, 0xc328000
	s_nop 0
	v_addc_co_u32_e32 v183, vcc, 0, v169, vcc
	s_bitcmp1_b32 s1, 0
	v_add_co_u32_e32 v186, vcc, s3, v168
	s_cselect_b32 s3, 0x2200, 0
	s_bitcmp1_b32 s2, 0
	s_cselect_b32 s2, 0x2200, 0
	s_add_i32 s3, s3, 0
	v_add_u32_e32 v194, s3, v178
	v_add_u32_e32 v185, v194, v167
	v_addc_co_u32_e32 v187, vcc, 0, v169, vcc
	v_add_u32_e32 v185, v185, v150
	global_load_dwordx4 v[94:97], v[94:95], off offset:1024
	v_lshl_add_u64 v[174:175], s[10:11], 0, v[160:161]
	global_load_dwordx4 v[98:101], v[98:99], off
	s_nop 0
	global_load_ushort v181, v[126:127], off
	s_nop 0
	global_load_dwordx4 v[126:129], v[174:175], off offset:-520
	s_mov_b32 s3, 0xc201000
	global_load_ushort v182, v[182:183], off offset:1024
	s_add_i32 s2, s2, 0
	global_load_ushort v183, v[186:187], off offset:2048
	ds_read_b128 v[186:189], v185
	s_waitcnt lgkmcnt(0)
	v_mfma_f32_16x16x32_bf16 v[42:45], v[42:45], v[186:189], v[142:145]
	s_nop 2
	ds_read_b128 v[142:145], v185 offset:64
	v_add_u32_e32 v190, s2, v178
	s_mov_b32 s2, 0xc3b0000
	s_waitcnt lgkmcnt(0)
	v_mfma_f32_16x16x32_bf16 v[34:37], v[34:37], v[142:145], v[42:45]
	v_add3_u32 v195, v190, v167, v150
	s_nop 1
	ds_read_b128 v[42:45], v185 offset:128
	s_waitcnt lgkmcnt(0)
	v_mfma_f32_16x16x32_bf16 v[34:37], v[38:41], v[42:45], v[34:37]
	ds_read_b128 v[38:41], v185 offset:192
	s_cmp_gt_u32 s1, 59
	s_waitcnt lgkmcnt(0)
	v_mfma_f32_16x16x32_bf16 v[26:29], v[26:29], v[38:41], v[34:37]
	s_cselect_b64 s[12:13], -1, 0
	s_nop 6
	v_bfe_u32 v34, v26, 16, 1
	v_add3_u32 v26, v26, v34, s72
	v_lshl_add_u64 v[34:35], s[10:11], 0, v[162:163]
	v_add_co_u32_e32 v36, vcc, s3, v34
	s_mov_b32 s3, 0xc204000
	s_nop 0
	v_addc_co_u32_e32 v37, vcc, 0, v35, vcc
	global_store_short_d16_hi v[36:37], v26, off offset:3072
	v_bfe_u32 v26, v27, 16, 1
	v_add3_u32 v36, v27, v26, s72
	v_add_co_u32_e32 v26, vcc, s3, v34
	s_mov_b32 s3, 0xc206000
	s_nop 0
	v_addc_co_u32_e32 v27, vcc, 0, v35, vcc
	global_store_short_d16_hi v[26:27], v36, off
	v_bfe_u32 v26, v28, 16, 1
	v_add3_u32 v28, v28, v26, s72
	v_add_co_u32_e32 v26, vcc, s3, v34
	s_mov_b32 s3, 0xc208000
	s_nop 0
	v_addc_co_u32_e32 v27, vcc, 0, v35, vcc
	global_store_short_d16_hi v[26:27], v28, off offset:1024
	v_bfe_u32 v26, v29, 16, 1
	v_add3_u32 v28, v29, v26, s72
	v_add_co_u32_e32 v26, vcc, s3, v34
	v_add3_u32 v34, v190, v179, v180
	s_nop 0
	v_addc_co_u32_e32 v27, vcc, 0, v35, vcc
	global_store_short_d16_hi v[26:27], v28, off offset:2048
	s_waitcnt vmcnt(30)
	v_pk_mul_f32 v[26:27], v[30:31], v[138:139]
	v_pk_mul_f32 v[28:29], v[32:33], v[140:141]
	s_nop 1
	v_mfma_f32_16x16x32_bf16 v[18:21], v[2:5], v[18:21], v[26:29]
	v_mfma_f32_16x16x32_bf16 v[138:141], v[6:9], v[22:25], v[18:21]
	s_nop 7
	v_and_b32_sdwa v19, v138, v220 dst_sel:DWORD dst_unused:UNUSED_PAD src0_sel:WORD_1 src1_sel:DWORD
	v_add3_u32 v20, v138, v19, s72
	v_and_b32_sdwa v19, v141, v220 dst_sel:DWORD dst_unused:UNUSED_PAD src0_sel:WORD_1 src1_sel:DWORD
	v_and_b32_sdwa v21, v139, v220 dst_sel:DWORD dst_unused:UNUSED_PAD src0_sel:WORD_1 src1_sel:DWORD
	v_and_b32_sdwa v18, v140, v220 dst_sel:DWORD dst_unused:UNUSED_PAD src0_sel:WORD_1 src1_sel:DWORD
	v_add3_u32 v19, v141, v19, s72
	v_add3_u32 v21, v139, v21, s72
	v_add3_u32 v18, v140, v18, s72
	v_and_b32_e32 v19, 0xffff0000, v19
	v_and_b32_e32 v21, 0xffff0000, v21
	v_or_b32_sdwa v19, v19, v18 dst_sel:DWORD dst_unused:UNUSED_PAD src0_sel:DWORD src1_sel:WORD_1
	v_or_b32_sdwa v18, v21, v20 dst_sel:DWORD dst_unused:UNUSED_PAD src0_sel:DWORD src1_sel:WORD_1
	ds_write_b64 v34, v[18:19]
	v_pk_mul_f32 v[18:19], v[30:31], v[134:135]
	v_pk_mul_f32 v[20:21], v[32:33], v[136:137]
	s_waitcnt vmcnt(19)
	v_pk_mul_f32 v[140:141], v[76:77], v[140:141]
	v_pk_mul_f32 v[138:139], v[74:75], v[138:139]
	v_mfma_f32_16x16x32_bf16 v[2:5], v[2:5], v[10:13], v[18:21]
	v_mfma_f32_16x16x32_bf16 v[134:137], v[6:9], v[14:17], v[2:5]
	v_mfma_f32_16x16x32_bf16 v[138:141], v[58:61], v[62:65], v[138:141]
	v_mfma_f32_16x16x32_bf16 v[138:141], v[82:85], v[86:89], v[138:141]
	s_nop 5
	v_and_b32_sdwa v3, v134, v220 dst_sel:DWORD dst_unused:UNUSED_PAD src0_sel:WORD_1 src1_sel:DWORD
	v_add3_u32 v4, v134, v3, s72
	v_and_b32_sdwa v3, v137, v220 dst_sel:DWORD dst_unused:UNUSED_PAD src0_sel:WORD_1 src1_sel:DWORD
	v_and_b32_sdwa v5, v135, v220 dst_sel:DWORD dst_unused:UNUSED_PAD src0_sel:WORD_1 src1_sel:DWORD
	v_and_b32_sdwa v2, v136, v220 dst_sel:DWORD dst_unused:UNUSED_PAD src0_sel:WORD_1 src1_sel:DWORD
	v_add3_u32 v3, v137, v3, s72
	v_add3_u32 v5, v135, v5, s72
	v_add3_u32 v2, v136, v2, s72
	v_and_b32_e32 v3, 0xffff0000, v3
	v_and_b32_e32 v5, 0xffff0000, v5
	v_or_b32_sdwa v3, v3, v2 dst_sel:DWORD dst_unused:UNUSED_PAD src0_sel:DWORD src1_sel:WORD_1
	v_or_b32_sdwa v2, v5, v4 dst_sel:DWORD dst_unused:UNUSED_PAD src0_sel:DWORD src1_sel:WORD_1
	ds_write_b64 v34, v[2:3] offset:4352
	v_add_co_u32_e32 v2, vcc, s2, v176
	s_waitcnt lgkmcnt(0)
	s_barrier
	s_nop 0
	v_addc_co_u32_e32 v3, vcc, 0, v177, vcc
	s_mov_b32 s2, 0xc3b9000
	global_load_dwordx4 v[42:45], v[2:3], off offset:3072
	v_add_co_u32_e32 v2, vcc, s2, v176
	s_mov_b32 s2, 0xc3c2000
	s_nop 0
	v_addc_co_u32_e32 v3, vcc, 0, v177, vcc
	global_load_dwordx4 v[34:37], v[2:3], off offset:3072
	v_add_co_u32_e32 v2, vcc, s2, v176
	s_mov_b32 s2, 0xc3cb000
	s_nop 0
	v_addc_co_u32_e32 v3, vcc, 0, v177, vcc
	global_load_dwordx4 v[38:41], v[2:3], off offset:3072
	v_add_co_u32_e32 v2, vcc, s2, v176
	s_mov_b32 s2, 0xc3c3000
	s_nop 0
	v_addc_co_u32_e32 v3, vcc, 0, v177, vcc
	global_load_dwordx4 v[26:29], v[2:3], off offset:3072
	v_add_co_u32_e32 v2, vcc, s64, v172
	v_pk_mul_f32 v[136:137], v[76:77], v[136:137]
	s_nop 0
	v_addc_co_u32_e32 v3, vcc, 0, v173, vcc
	v_add_co_u32_e32 v6, vcc, s64, v170
	global_load_dwordx4 v[2:5], v[2:3], off
	s_nop 0
	v_addc_co_u32_e32 v7, vcc, 0, v171, vcc
	global_load_dwordx4 v[18:21], v[6:7], off offset:1024
	v_add_co_u32_e32 v6, vcc, s2, v170
	s_mov_b32 s2, 0xc3ba000
	s_nop 0
	v_addc_co_u32_e32 v7, vcc, 0, v171, vcc
	global_load_dwordx4 v[10:13], v[6:7], off offset:1024
	v_add_co_u32_e32 v6, vcc, s2, v172
	v_pk_mul_f32 v[134:135], v[74:75], v[134:135]
	s_nop 0
	v_addc_co_u32_e32 v7, vcc, 0, v173, vcc
	v_add_co_u32_e32 v14, vcc, s2, v170
	s_mov_b32 s2, 0xc3cc000
	s_nop 0
	v_addc_co_u32_e32 v15, vcc, 0, v171, vcc
	global_load_dwordx4 v[22:25], v[14:15], off offset:1024
	v_add_co_u32_e32 v14, vcc, s2, v170
	s_mov_b32 s2, 0xc3b4000
	s_nop 0
	v_addc_co_u32_e32 v15, vcc, 0, v171, vcc
	v_add_co_u32_e32 v30, vcc, s64, v168
	global_load_dwordx4 v[14:17], v[14:15], off offset:1024
	s_nop 0
	v_addc_co_u32_e32 v31, vcc, 0, v169, vcc
	global_load_ushort v142, v[30:31], off offset:3072
	v_add_co_u32_e32 v30, vcc, s2, v168
	s_mov_b32 s2, 0xc3b6000
	s_nop 0
	v_addc_co_u32_e32 v31, vcc, 0, v169, vcc
	v_add_co_u32_e32 v144, vcc, s2, v168
	s_mov_b32 s2, 0xc3b8000
	s_nop 0
	v_addc_co_u32_e32 v145, vcc, 0, v169, vcc
	v_add_co_u32_e32 v186, vcc, s2, v168
	global_load_dwordx4 v[6:9], v[6:7], off
	s_nop 0
	v_addc_co_u32_e32 v187, vcc, 0, v169, vcc
	global_load_ushort v143, v[30:31], off
	s_nop 0
	global_load_dwordx4 v[30:33], v[174:175], off offset:-8
	ds_read_b128 v[190:193], v195
	global_load_ushort v144, v[144:145], off offset:1024
	s_mov_b32 s2, 0xc291000
	global_load_ushort v145, v[186:187], off offset:2048
	s_waitcnt vmcnt(40)
	v_lshlrev_b32_e32 v186, 16, v149
	v_lshlrev_b32_e32 v188, 16, v151
	v_lshlrev_b32_e32 v189, 16, v166
	v_lshlrev_b32_e32 v187, 16, v164
	v_mfma_f32_16x16x32_bf16 v[134:137], v[58:61], v[66:69], v[134:137]
	s_waitcnt lgkmcnt(0)
	v_mfma_f32_16x16x32_bf16 v[186:189], v[70:73], v[190:193], v[186:189]
	ds_read_b128 v[190:193], v195 offset:64
	s_waitcnt lgkmcnt(0)
	v_mfma_f32_16x16x32_bf16 v[186:189], v[46:49], v[190:193], v[186:189]
	ds_read_b128 v[190:193], v195 offset:128
	s_waitcnt lgkmcnt(0)
	v_mfma_f32_16x16x32_bf16 v[186:189], v[50:53], v[190:193], v[186:189]
	ds_read_b128 v[190:193], v195 offset:192
	s_waitcnt lgkmcnt(0)
	v_mfma_f32_16x16x32_bf16 v[186:189], v[54:57], v[190:193], v[186:189]
	v_mfma_f32_16x16x32_bf16 v[134:137], v[82:85], v[78:81], v[134:137]
	s_nop 6
	v_bfe_u32 v190, v186, 16, 1
	v_add3_u32 v186, v186, v190, s72
	v_add_co_u32_e32 v190, vcc, s2, v168
	s_mov_b32 s2, 0xc294000
	s_nop 0
	v_addc_co_u32_e32 v191, vcc, 0, v169, vcc
	global_store_short_d16_hi v[190:191], v186, off offset:3072
	v_bfe_u32 v186, v187, 16, 1
	v_add3_u32 v190, v187, v186, s72
	v_add_co_u32_e32 v186, vcc, s2, v168
	s_mov_b32 s2, 0xc296000
	s_nop 0
	v_addc_co_u32_e32 v187, vcc, 0, v169, vcc
	global_store_short_d16_hi v[186:187], v190, off
	v_bfe_u32 v186, v188, 16, 1
	v_add3_u32 v188, v188, v186, s72
	v_add_co_u32_e32 v186, vcc, s2, v168
	s_mov_b32 s2, 0xc298000
	s_nop 0
	v_addc_co_u32_e32 v187, vcc, 0, v169, vcc
	global_store_short_d16_hi v[186:187], v188, off offset:1024
	v_bfe_u32 v186, v189, 16, 1
	v_add3_u32 v188, v189, v186, s72
	v_add_co_u32_e32 v186, vcc, s2, v168
	v_and_b32_sdwa v190, v139, v220 dst_sel:DWORD dst_unused:UNUSED_PAD src0_sel:WORD_1 src1_sel:DWORD
	s_nop 0
	v_addc_co_u32_e32 v187, vcc, 0, v169, vcc
	global_store_short_d16_hi v[186:187], v188, off offset:2048
	v_and_b32_sdwa v187, v138, v220 dst_sel:DWORD dst_unused:UNUSED_PAD src0_sel:WORD_1 src1_sel:DWORD
	v_add3_u32 v189, v138, v187, s72
	v_and_b32_sdwa v187, v141, v220 dst_sel:DWORD dst_unused:UNUSED_PAD src0_sel:WORD_1 src1_sel:DWORD
	v_and_b32_sdwa v186, v140, v220 dst_sel:DWORD dst_unused:UNUSED_PAD src0_sel:WORD_1 src1_sel:DWORD
	v_add3_u32 v187, v141, v187, s72
	v_add3_u32 v190, v139, v190, s72
	v_add3_u32 v186, v140, v186, s72
	v_and_b32_e32 v187, 0xffff0000, v187
	v_and_b32_e32 v190, 0xffff0000, v190
	v_add3_u32 v188, v194, v179, v180
	v_or_b32_sdwa v187, v187, v186 dst_sel:DWORD dst_unused:UNUSED_PAD src0_sel:DWORD src1_sel:WORD_1
	v_or_b32_sdwa v186, v190, v189 dst_sel:DWORD dst_unused:UNUSED_PAD src0_sel:DWORD src1_sel:WORD_1
	ds_write_b64 v188, v[186:187]
	v_and_b32_sdwa v187, v134, v220 dst_sel:DWORD dst_unused:UNUSED_PAD src0_sel:WORD_1 src1_sel:DWORD
	v_add3_u32 v189, v134, v187, s72
	v_and_b32_sdwa v187, v137, v220 dst_sel:DWORD dst_unused:UNUSED_PAD src0_sel:WORD_1 src1_sel:DWORD
	v_and_b32_sdwa v190, v135, v220 dst_sel:DWORD dst_unused:UNUSED_PAD src0_sel:WORD_1 src1_sel:DWORD
	v_and_b32_sdwa v186, v136, v220 dst_sel:DWORD dst_unused:UNUSED_PAD src0_sel:WORD_1 src1_sel:DWORD
	v_add3_u32 v187, v137, v187, s72
	v_add3_u32 v190, v135, v190, s72
	v_add3_u32 v186, v136, v186, s72
	v_and_b32_e32 v187, 0xffff0000, v187
	v_and_b32_e32 v190, 0xffff0000, v190
	v_or_b32_sdwa v187, v187, v186 dst_sel:DWORD dst_unused:UNUSED_PAD src0_sel:DWORD src1_sel:WORD_1
	v_or_b32_sdwa v186, v190, v189 dst_sel:DWORD dst_unused:UNUSED_PAD src0_sel:DWORD src1_sel:WORD_1
	ds_write_b64 v188, v[186:187] offset:4352
	s_waitcnt lgkmcnt(0)
	s_barrier
	s_and_b64 vcc, exec, s[12:13]
	s_cbranch_vccnz .Lhg_scan_last
	v_add_co_u32_e32 v70, vcc, 0xc440000, v176
	s_mov_b32 s2, 0xc441000
	s_nop 0
	v_addc_co_u32_e32 v71, vcc, 0, v177, vcc
	v_add_co_u32_e32 v46, vcc, 0xc449000, v176
	s_nop 1
	v_addc_co_u32_e32 v47, vcc, 0, v177, vcc
	v_add_co_u32_e32 v50, vcc, 0xc452000, v176
	s_nop 1
	v_addc_co_u32_e32 v51, vcc, 0, v177, vcc
	v_add_co_u32_e32 v54, vcc, 0xc45b000, v176
	global_load_dwordx4 v[46:49], v[46:47], off offset:3072
	s_nop 0
	global_load_dwordx4 v[50:53], v[50:51], off offset:3072
	v_addc_co_u32_e32 v55, vcc, 0, v177, vcc
	v_add_co_u32_e32 v58, vcc, 0xc441000, v172
	s_nop 1
	v_addc_co_u32_e32 v59, vcc, 0, v173, vcc
	v_add_co_u32_e32 v62, vcc, 0xc441000, v170
	global_load_dwordx4 v[54:57], v[54:55], off offset:3072
	s_nop 0
	global_load_dwordx4 v[58:61], v[58:59], off
	v_addc_co_u32_e32 v63, vcc, 0, v171, vcc
	v_add_co_u32_e32 v66, vcc, 0xc453000, v170
	s_nop 1
	v_addc_co_u32_e32 v67, vcc, 0, v171, vcc
	v_add_co_u32_e32 v82, vcc, 0xc44a000, v172
	global_load_dwordx4 v[62:65], v[62:63], off offset:1024
	s_nop 0
	global_load_dwordx4 v[66:69], v[66:67], off offset:1024
	v_addc_co_u32_e32 v83, vcc, 0, v173, vcc
	v_add_co_u32_e32 v86, vcc, 0xc44a000, v170
	global_load_dwordx4 v[70:73], v[70:71], off offset:3072
	s_nop 0
	global_load_dwordx4 v[74:77], v[174:175], off offset:504
	v_addc_co_u32_e32 v87, vcc, 0, v171, vcc
	v_add_co_u32_e32 v78, vcc, 0xc45c000, v170
	s_nop 1
	v_addc_co_u32_e32 v79, vcc, 0, v171, vcc
	v_add_co_u32_e32 v84, vcc, 0xc444000, v168
	s_nop 1
	v_addc_co_u32_e32 v85, vcc, 0, v169, vcc
	v_add_co_u32_e32 v88, vcc, s2, v168
	s_nop 1
	v_addc_co_u32_e32 v89, vcc, 0, v169, vcc
	v_add_co_u32_e32 v170, vcc, 0xc448000, v168
	s_nop 1
	v_addc_co_u32_e32 v171, vcc, 0, v169, vcc
	global_load_dwordx4 v[78:81], v[78:79], off offset:1024
	s_nop 0
	global_load_ushort v164, v[84:85], off
	global_load_ushort v149, v[88:89], off offset:3072
	global_load_ushort v166, v[170:171], off offset:2048
	v_add_co_u32_e32 v84, vcc, 0xc446000, v168
	v_addc_co_u32_e32 v85, vcc, 0, v169, vcc
	global_load_ushort v151, v[84:85], off offset:1024
	s_nop 0
	global_load_dwordx4 v[82:85], v[82:83], off
	s_nop 0
	global_load_dwordx4 v[86:89], v[86:87], off offset:1024
	s_branch .LBB0_265

; __device__ __forceinline__ int ptid_(int wave) { int l_; asm volatile("v_mbcnt_lo_u32_b32 %0, -1, 0\n\tv_mbcnt_hi_u32_b32 %0, -1, %0" : "=v"(l_)); return (wave << 6) | l_; }
; __device__ void dn_scan_block(const Params& p, int L, int item) {
;   float* misc = (float*)(p.ws + MISC_OFF);
;   bfu* pab = (bfu*)(p.ws + PAB_OFF);
;   const int bh = item >> 2, qt = item & 3;
;   int tid = ptid_(p.tid); asm volatile("" : "+v"(tid));
;   const int w = tid >> 6, lane = tid & 63, c = lane & 15, q = lane >> 4;
;   const int rt = w >> 1, ct = w & 1, dt = w;
;   bfu* St = (bfu*)smem;
;   bfu* ut = St + 2 * 2176;
;   const int b = bh >> 2, h = bh & 3;
;   __syncthreads();
;   for (int i = tid; i < 2 * 2176; i += NTHR) St[i] = 0;
;   f32x4 Sacc[2];
;   Sacc[0] = (f32x4){0.f, 0.f, 0.f, 0.f}; Sacc[1] = Sacc[0];
;     ...
;   DN_DECL(A) DN_DECL(B) DN_DECL(C)
;     ...
;   DN_LOAD(A, 0); DN_LOAD(B, 1);
;   __syncthreads();
.LBB0_273:
	s_or_b64 exec, exec, s[12:13]
	v_mbcnt_lo_u32_b32 v0, -1, 0
	v_mbcnt_hi_u32_b32 v0, -1, v0
	s_lshr_b32 s1, s33, 6
	s_and_b32 s2, s1, 3
	s_lshr_b32 s3, s1, 2
	v_and_b32_e32 v2, 15, v0
	v_lshrrev_b32_e32 v3, 4, v0
	v_lshlrev_b32_e32 v4, 4, v0
	s_lshl_b32 s12, s2, 12
	s_lshl_b32 s13, s3, 15
	s_add_i32 s12, s12, s13
	v_add_u32_e32 v196, s12, v4
	s_lshl_b32 s12, s1, 11
	s_add_i32 s12, s12, 0xc000
	v_add_u32_e32 v197, s12, v4
	s_lshl_b32 s12, s2, 3
	s_lshl_b32 s13, s21, 1
	s_add_i32 s12, s12, s13
	s_lshl_b32 s12, s12, 9
	s_add_i32 s12, s12, 0x4000
	v_lshl_add_u32 v198, v0, 3, s12
	s_lshl_b32 s12, s2, 11
	s_add_i32 s12, s12, 0x10000
	v_add_u32_e32 v5, s12, v4
	s_cmp_eq_u32 s3, 1
	s_cselect_b64 vcc, -1, 0
	v_cndmask_b32_e32 v198, v198, v5, vcc
	s_and_b32 s12, s0, 3
	s_lshl_b32 s12, s12, 7
	s_lshl_b32 s13, s21, 5
	s_add_i32 s12, s12, s13
	s_lshl_b32 s12, s12, 1
	s_mul_i32 s13, s2, 0x1c000
	s_add_i32 s12, s12, s13
	v_mul_u32_u24_e32 v5, 0x7000, v3
	v_lshl_add_u32 v5, v2, 1, v5
	v_add_u32_e32 v202, s12, v5
	v_add_u32_e32 v203, 0x1c00, v202
	v_add_u32_e32 v204, 0x3800, v202
	v_add_u32_e32 v205, 0x5400, v202
	v_mul_u32_u24_e32 v5, 0x110, v2
	v_lshl_add_u32 v206, v3, 4, v5
	v_lshl_add_u32 v6, v3, 3, v5
	s_lshl_b32 s12, s1, 5
	v_add_u32_e32 v209, s12, v6
	v_mul_u32_u24_e32 v5, 0x90, v2
	v_lshl_add_u32 v208, v3, 4, v5
	v_lshl_add_u32 v6, v3, 3, v5
	s_lshl_b32 s12, s2, 5
	s_add_i32 s12, s12, 0x2200
	v_add_u32_e32 v207, s12, v6
	s_lshl_b32 s42, s0, 6
	s_lshl_b32 s1, s0, 8
	s_add_u32 s36, s52, 0x231000
	s_addc_u32 s37, s53, 0
	s_add_u32 s36, s36, s1
	s_addc_u32 s37, s37, 0
	s_mul_i32 s1, s40, 0x1c00000
	s_add_u32 s18, s10, s1
	s_addc_u32 s19, s11, 0
	s_add_u32 s18, s18, 0x11200000
	s_addc_u32 s19, s19, 0
	s_mov_b32 s22, 0
	v_mov_b32_e32 v148, 0
	v_mov_b32_e32 v149, 0
	v_mov_b32_e32 v150, 0
	v_mov_b32_e32 v151, 0
	v_mov_b32_e32 v152, 0
	v_mov_b32_e32 v153, 0
	v_mov_b32_e32 v154, 0
	v_mov_b32_e32 v155, 0
	s_cmp_eq_u32 s3, 1
	s_cbranch_scc1 .Ldn_scan_o
	s_mov_b32 s0, 0
	s_add_i32 s1, s42, s0
	s_lshl_b32 s2, s0, 2
	s_add_u32 s14, s36, s2
	s_addc_u32 s15, s37, 0
	s_add_i32 s2, s1, 0xfffff8e4
	s_cmpk_lt_i32 s1, 0x71c
	s_cselect_b32 s1, s1, s2
	s_cselect_b32 s2, s8, s16
	s_cselect_b32 s3, s9, s17
	s_mul_hi_u32 s13, s1, 0x12000
	s_mul_i32 s12, s1, 0x12000
	s_add_u32 s12, s2, s12
	s_addc_u32 s13, s3, s13
	global_load_dwordx2 v[26:27], v198, s[12:13]
	global_load_dwordx2 v[28:29], v198, s[12:13] offset:512
	global_load_dword v34, v1, s[14:15]
	global_load_dwordx4 v[2:5], v196, s[12:13]
	global_load_dwordx4 v[6:9], v196, s[12:13] offset:1024
	global_load_dwordx4 v[10:13], v196, s[12:13] offset:2048
	global_load_dwordx4 v[14:17], v196, s[12:13] offset:3072
	global_load_dwordx4 v[18:21], v197, s[12:13]
	global_load_dwordx4 v[22:25], v197, s[12:13] offset:1024
	s_mov_b32 s0, 1
	s_add_i32 s1, s42, s0
	s_lshl_b32 s2, s0, 2
	s_add_u32 s14, s36, s2
	s_addc_u32 s15, s37, 0
	s_add_i32 s2, s1, 0xfffff8e4
	s_cmpk_lt_i32 s1, 0x71c
	s_cselect_b32 s1, s1, s2
	s_cselect_b32 s2, s8, s16
	s_cselect_b32 s3, s9, s17
	s_mul_hi_u32 s13, s1, 0x12000
	s_mul_i32 s12, s1, 0x12000
	s_add_u32 s12, s2, s12
	s_addc_u32 s13, s3, s13
	global_load_dwordx2 v[60:61], v198, s[12:13]
	global_load_dwordx2 v[62:63], v198, s[12:13] offset:512
	global_load_dword v68, v1, s[14:15]
	global_load_dwordx4 v[36:39], v196, s[12:13]
	global_load_dwordx4 v[40:43], v196, s[12:13] offset:1024
	global_load_dwordx4 v[44:47], v196, s[12:13] offset:2048
	global_load_dwordx4 v[48:51], v196, s[12:13] offset:3072
	global_load_dwordx4 v[52:55], v197, s[12:13]
	global_load_dwordx4 v[56:59], v197, s[12:13] offset:1024
	s_mov_b32 s0, 2
	s_add_i32 s1, s42, s0
	s_lshl_b32 s2, s0, 2
	s_add_u32 s14, s36, s2
	s_addc_u32 s15, s37, 0
	s_add_i32 s2, s1, 0xfffff8e4
	s_cmpk_lt_i32 s1, 0x71c
	s_cselect_b32 s1, s1, s2
	s_cselect_b32 s2, s8, s16
	s_cselect_b32 s3, s9, s17
	s_mul_hi_u32 s13, s1, 0x12000
	s_mul_i32 s12, s1, 0x12000
	s_add_u32 s12, s2, s12
	s_addc_u32 s13, s3, s13
	global_load_dwordx2 v[94:95], v198, s[12:13]
	global_load_dwordx2 v[96:97], v198, s[12:13] offset:512
	global_load_dword v102, v1, s[14:15]
	global_load_dwordx4 v[70:73], v196, s[12:13]
	global_load_dwordx4 v[74:77], v196, s[12:13] offset:1024
	global_load_dwordx4 v[78:81], v196, s[12:13] offset:2048
	global_load_dwordx4 v[82:85], v196, s[12:13] offset:3072
	global_load_dwordx4 v[86:89], v197, s[12:13]
	global_load_dwordx4 v[90:93], v197, s[12:13] offset:1024
	s_waitcnt lgkmcnt(0)
	s_barrier
.Ldn_scan_loop_u:
	s_add_i32 s0, s22, 3
	s_min_u32 s0, s0, 63
	s_add_i32 s1, s42, s0
	s_lshl_b32 s2, s0, 2
	s_add_u32 s14, s36, s2
	s_addc_u32 s15, s37, 0
	s_add_i32 s2, s1, 0xfffff8e4
	s_cmpk_lt_i32 s1, 0x71c
	s_cselect_b32 s1, s1, s2
	s_cselect_b32 s2, s8, s16
	s_cselect_b32 s3, s9, s17
	s_mul_hi_u32 s13, s1, 0x12000
	s_mul_i32 s12, s1, 0x12000
	s_add_u32 s12, s2, s12
	s_addc_u32 s13, s3, s13
	global_load_dwordx2 v[128:129], v198, s[12:13]
	global_load_dwordx2 v[130:131], v198, s[12:13] offset:512
	global_load_dword v136, v1, s[14:15]
	global_load_dwordx4 v[104:107], v196, s[12:13]
	global_load_dwordx4 v[108:111], v196, s[12:13] offset:1024
	global_load_dwordx4 v[112:115], v196, s[12:13] offset:2048
	global_load_dwordx4 v[116:119], v196, s[12:13] offset:3072
	global_load_dwordx4 v[120:123], v197, s[12:13]
	global_load_dwordx4 v[124:127], v197, s[12:13] offset:1024
	ds_read_b128 v[156:159], v206 offset:0
	ds_read_b128 v[172:175], v206 offset:4352
	ds_read_b128 v[160:163], v206 offset:64
	ds_read_b128 v[176:179], v206 offset:4416
	ds_read_b128 v[164:167], v206 offset:128
	ds_read_b128 v[180:183], v206 offset:4480
	ds_read_b128 v[168:171], v206 offset:192
	ds_read_b128 v[184:187], v206 offset:4544
	s_waitcnt vmcnt(27)
	v_lshlrev_b32_e32 v140, 16, v26
	v_and_b32_e32 v141, 0xffff0000, v26
	v_lshlrev_b32_e32 v142, 16, v27
	v_and_b32_e32 v143, 0xffff0000, v27
	v_lshlrev_b32_e32 v144, 16, v28
	v_and_b32_e32 v145, 0xffff0000, v28
	v_lshlrev_b32_e32 v146, 16, v29
	v_and_b32_e32 v147, 0xffff0000, v29
	v_pk_mul_f32 v[148:149], v[34:35], v[148:149] op_sel_hi:[0,1]
	v_pk_mul_f32 v[150:151], v[34:35], v[150:151] op_sel_hi:[0,1]
	v_pk_mul_f32 v[152:153], v[34:35], v[152:153] op_sel_hi:[0,1]
	v_pk_mul_f32 v[154:155], v[34:35], v[154:155] op_sel_hi:[0,1]
	s_waitcnt lgkmcnt(7)
	v_mfma_f32_16x16x32_bf16 v[140:143], v[2:5], v[156:159], v[140:143]
	s_waitcnt lgkmcnt(6)
	v_mfma_f32_16x16x32_bf16 v[144:147], v[2:5], v[172:175], v[144:147]
	s_waitcnt lgkmcnt(5)
	v_mfma_f32_16x16x32_bf16 v[140:143], v[6:9], v[160:163], v[140:143]
	s_waitcnt lgkmcnt(4)
	v_mfma_f32_16x16x32_bf16 v[144:147], v[6:9], v[176:179], v[144:147]
	s_waitcnt lgkmcnt(3)
	v_mfma_f32_16x16x32_bf16 v[140:143], v[10:13], v[164:167], v[140:143]
	s_waitcnt lgkmcnt(2)
	v_mfma_f32_16x16x32_bf16 v[144:147], v[10:13], v[180:183], v[144:147]
	s_waitcnt lgkmcnt(1)
	v_mfma_f32_16x16x32_bf16 v[140:143], v[14:17], v[168:171], v[140:143]
	s_waitcnt lgkmcnt(0)
	v_mfma_f32_16x16x32_bf16 v[144:147], v[14:17], v[184:187], v[144:147]
	s_nop 6
	v_cvt_pk_bf16_f32 v188, v140, v141
	v_cvt_pk_bf16_f32 v189, v142, v143
	v_cvt_pk_bf16_f32 v190, v144, v145
	v_cvt_pk_bf16_f32 v191, v146, v147
	ds_write_b64 v207, v[188:189]
	ds_write_b64 v207, v[190:191] offset:2304
	s_waitcnt lgkmcnt(0)
	s_barrier
	ds_read_b128 v[156:159], v208 offset:8704
	ds_read_b128 v[172:175], v208 offset:11008
	ds_read_b128 v[160:163], v208 offset:8768
	ds_read_b128 v[176:179], v208 offset:11072
	s_waitcnt lgkmcnt(3)
	v_mfma_f32_16x16x32_bf16 v[148:151], v[18:21], v[156:159], v[148:151]
	s_waitcnt lgkmcnt(2)
	v_mfma_f32_16x16x32_bf16 v[152:155], v[18:21], v[172:175], v[152:155]
	s_waitcnt lgkmcnt(1)
	v_mfma_f32_16x16x32_bf16 v[148:151], v[22:25], v[160:163], v[148:151]
	s_waitcnt lgkmcnt(0)
	v_mfma_f32_16x16x32_bf16 v[152:155], v[22:25], v[176:179], v[152:155]
	s_nop 6
	v_cvt_pk_bf16_f32 v188, v148, v149
	v_cvt_pk_bf16_f32 v189, v150, v151
	v_cvt_pk_bf16_f32 v190, v152, v153
	v_cvt_pk_bf16_f32 v191, v154, v155
	ds_write_b64 v209, v[188:189]
	ds_write_b64 v209, v[190:191] offset:4352
	s_add_i32 s22, s22, 1
	s_waitcnt lgkmcnt(0)
	s_barrier
	s_add_i32 s0, s22, 3
	s_min_u32 s0, s0, 63
	s_add_i32 s1, s42, s0
	s_lshl_b32 s2, s0, 2
	s_add_u32 s14, s36, s2
	s_addc_u32 s15, s37, 0
	s_add_i32 s2, s1, 0xfffff8e4
	s_cmpk_lt_i32 s1, 0x71c
	s_cselect_b32 s1, s1, s2
	s_cselect_b32 s2, s8, s16
	s_cselect_b32 s3, s9, s17
	s_mul_hi_u32 s13, s1, 0x12000
	s_mul_i32 s12, s1, 0x12000
	s_add_u32 s12, s2, s12
	s_addc_u32 s13, s3, s13
	global_load_dwordx2 v[26:27], v198, s[12:13]
	global_load_dwordx2 v[28:29], v198, s[12:13] offset:512
	global_load_dword v34, v1, s[14:15]
	global_load_dwordx4 v[2:5], v196, s[12:13]
	global_load_dwordx4 v[6:9], v196, s[12:13] offset:1024
	global_load_dwordx4 v[10:13], v196, s[12:13] offset:2048
	global_load_dwordx4 v[14:17], v196, s[12:13] offset:3072
	global_load_dwordx4 v[18:21], v197, s[12:13]
	global_load_dwordx4 v[22:25], v197, s[12:13] offset:1024
	ds_read_b128 v[156:159], v206 offset:0
	ds_read_b128 v[172:175], v206 offset:4352
	ds_read_b128 v[160:163], v206 offset:64
	ds_read_b128 v[176:179], v206 offset:4416
	ds_read_b128 v[164:167], v206 offset:128
	ds_read_b128 v[180:183], v206 offset:4480
	ds_read_b128 v[168:171], v206 offset:192
	ds_read_b128 v[184:187], v206 offset:4544
	s_waitcnt vmcnt(27)
	v_lshlrev_b32_e32 v140, 16, v60
	v_and_b32_e32 v141, 0xffff0000, v60
	v_lshlrev_b32_e32 v142, 16, v61
	v_and_b32_e32 v143, 0xffff0000, v61
	v_lshlrev_b32_e32 v144, 16, v62
	v_and_b32_e32 v145, 0xffff0000, v62
	v_lshlrev_b32_e32 v146, 16, v63
	v_and_b32_e32 v147, 0xffff0000, v63
	v_pk_mul_f32 v[148:149], v[68:69], v[148:149] op_sel_hi:[0,1]
	v_pk_mul_f32 v[150:151], v[68:69], v[150:151] op_sel_hi:[0,1]
	v_pk_mul_f32 v[152:153], v[68:69], v[152:153] op_sel_hi:[0,1]
	v_pk_mul_f32 v[154:155], v[68:69], v[154:155] op_sel_hi:[0,1]
	s_waitcnt lgkmcnt(7)
	v_mfma_f32_16x16x32_bf16 v[140:143], v[36:39], v[156:159], v[140:143]
	s_waitcnt lgkmcnt(6)
	v_mfma_f32_16x16x32_bf16 v[144:147], v[36:39], v[172:175], v[144:147]
	s_waitcnt lgkmcnt(5)
	v_mfma_f32_16x16x32_bf16 v[140:143], v[40:43], v[160:163], v[140:143]
	s_waitcnt lgkmcnt(4)
	v_mfma_f32_16x16x32_bf16 v[144:147], v[40:43], v[176:179], v[144:147]
	s_waitcnt lgkmcnt(3)
	v_mfma_f32_16x16x32_bf16 v[140:143], v[44:47], v[164:167], v[140:143]
	s_waitcnt lgkmcnt(2)
	v_mfma_f32_16x16x32_bf16 v[144:147], v[44:47], v[180:183], v[144:147]
	s_waitcnt lgkmcnt(1)
	v_mfma_f32_16x16x32_bf16 v[140:143], v[48:51], v[168:171], v[140:143]
	s_waitcnt lgkmcnt(0)
	v_mfma_f32_16x16x32_bf16 v[144:147], v[48:51], v[184:187], v[144:147]
	s_nop 6
	v_cvt_pk_bf16_f32 v188, v140, v141
	v_cvt_pk_bf16_f32 v189, v142, v143
	v_cvt_pk_bf16_f32 v190, v144, v145
	v_cvt_pk_bf16_f32 v191, v146, v147
	ds_write_b64 v207, v[188:189]
	ds_write_b64 v207, v[190:191] offset:2304
	s_waitcnt lgkmcnt(0)
	s_barrier
	ds_read_b128 v[156:159], v208 offset:8704
	ds_read_b128 v[172:175], v208 offset:11008
	ds_read_b128 v[160:163], v208 offset:8768
	ds_read_b128 v[176:179], v208 offset:11072
	s_waitcnt lgkmcnt(3)
	v_mfma_f32_16x16x32_bf16 v[148:151], v[52:55], v[156:159], v[148:151]
	s_waitcnt lgkmcnt(2)
	v_mfma_f32_16x16x32_bf16 v[152:155], v[52:55], v[172:175], v[152:155]
	s_waitcnt lgkmcnt(1)
	v_mfma_f32_16x16x32_bf16 v[148:151], v[56:59], v[160:163], v[148:151]
	s_waitcnt lgkmcnt(0)
	v_mfma_f32_16x16x32_bf16 v[152:155], v[56:59], v[176:179], v[152:155]
	s_nop 6
	v_cvt_pk_bf16_f32 v188, v148, v149
	v_cvt_pk_bf16_f32 v189, v150, v151
	v_cvt_pk_bf16_f32 v190, v152, v153
	v_cvt_pk_bf16_f32 v191, v154, v155
	ds_write_b64 v209, v[188:189]
	ds_write_b64 v209, v[190:191] offset:4352
	s_add_i32 s22, s22, 1
	s_waitcnt lgkmcnt(0)
	s_barrier
	s_add_i32 s0, s22, 3
	s_min_u32 s0, s0, 63
	s_add_i32 s1, s42, s0
	s_lshl_b32 s2, s0, 2
	s_add_u32 s14, s36, s2
	s_addc_u32 s15, s37, 0
	s_add_i32 s2, s1, 0xfffff8e4
	s_cmpk_lt_i32 s1, 0x71c
	s_cselect_b32 s1, s1, s2
	s_cselect_b32 s2, s8, s16
	s_cselect_b32 s3, s9, s17
	s_mul_hi_u32 s13, s1, 0x12000
	s_mul_i32 s12, s1, 0x12000
	s_add_u32 s12, s2, s12
	s_addc_u32 s13, s3, s13
	global_load_dwordx2 v[60:61], v198, s[12:13]
	global_load_dwordx2 v[62:63], v198, s[12:13] offset:512
	global_load_dword v68, v1, s[14:15]
	global_load_dwordx4 v[36:39], v196, s[12:13]
	global_load_dwordx4 v[40:43], v196, s[12:13] offset:1024
	global_load_dwordx4 v[44:47], v196, s[12:13] offset:2048
	global_load_dwordx4 v[48:51], v196, s[12:13] offset:3072
	global_load_dwordx4 v[52:55], v197, s[12:13]
	global_load_dwordx4 v[56:59], v197, s[12:13] offset:1024
	ds_read_b128 v[156:159], v206 offset:0
	ds_read_b128 v[172:175], v206 offset:4352
	ds_read_b128 v[160:163], v206 offset:64
	ds_read_b128 v[176:179], v206 offset:4416
	ds_read_b128 v[164:167], v206 offset:128
	ds_read_b128 v[180:183], v206 offset:4480
	ds_read_b128 v[168:171], v206 offset:192
	ds_read_b128 v[184:187], v206 offset:4544
	s_waitcnt vmcnt(27)
	v_lshlrev_b32_e32 v140, 16, v94
	v_and_b32_e32 v141, 0xffff0000, v94
	v_lshlrev_b32_e32 v142, 16, v95
	v_and_b32_e32 v143, 0xffff0000, v95
	v_lshlrev_b32_e32 v144, 16, v96
	v_and_b32_e32 v145, 0xffff0000, v96
	v_lshlrev_b32_e32 v146, 16, v97
	v_and_b32_e32 v147, 0xffff0000, v97
	v_pk_mul_f32 v[148:149], v[102:103], v[148:149] op_sel_hi:[0,1]
	v_pk_mul_f32 v[150:151], v[102:103], v[150:151] op_sel_hi:[0,1]
	v_pk_mul_f32 v[152:153], v[102:103], v[152:153] op_sel_hi:[0,1]
	v_pk_mul_f32 v[154:155], v[102:103], v[154:155] op_sel_hi:[0,1]
	s_waitcnt lgkmcnt(7)
	v_mfma_f32_16x16x32_bf16 v[140:143], v[70:73], v[156:159], v[140:143]
	s_waitcnt lgkmcnt(6)
	v_mfma_f32_16x16x32_bf16 v[144:147], v[70:73], v[172:175], v[144:147]
	s_waitcnt lgkmcnt(5)
	v_mfma_f32_16x16x32_bf16 v[140:143], v[74:77], v[160:163], v[140:143]
	s_waitcnt lgkmcnt(4)
	v_mfma_f32_16x16x32_bf16 v[144:147], v[74:77], v[176:179], v[144:147]
	s_waitcnt lgkmcnt(3)
	v_mfma_f32_16x16x32_bf16 v[140:143], v[78:81], v[164:167], v[140:143]
	s_waitcnt lgkmcnt(2)
	v_mfma_f32_16x16x32_bf16 v[144:147], v[78:81], v[180:183], v[144:147]
	s_waitcnt lgkmcnt(1)
	v_mfma_f32_16x16x32_bf16 v[140:143], v[82:85], v[168:171], v[140:143]
	s_waitcnt lgkmcnt(0)
	v_mfma_f32_16x16x32_bf16 v[144:147], v[82:85], v[184:187], v[144:147]
	s_nop 6
	v_cvt_pk_bf16_f32 v188, v140, v141
	v_cvt_pk_bf16_f32 v189, v142, v143
	v_cvt_pk_bf16_f32 v190, v144, v145
	v_cvt_pk_bf16_f32 v191, v146, v147
	ds_write_b64 v207, v[188:189]
	ds_write_b64 v207, v[190:191] offset:2304
	s_waitcnt lgkmcnt(0)
	s_barrier
	ds_read_b128 v[156:159], v208 offset:8704
	ds_read_b128 v[172:175], v208 offset:11008
	ds_read_b128 v[160:163], v208 offset:8768
	ds_read_b128 v[176:179], v208 offset:11072
	s_waitcnt lgkmcnt(3)
	v_mfma_f32_16x16x32_bf16 v[148:151], v[86:89], v[156:159], v[148:151]
	s_waitcnt lgkmcnt(2)
	v_mfma_f32_16x16x32_bf16 v[152:155], v[86:89], v[172:175], v[152:155]
	s_waitcnt lgkmcnt(1)
	v_mfma_f32_16x16x32_bf16 v[148:151], v[90:93], v[160:163], v[148:151]
	s_waitcnt lgkmcnt(0)
	v_mfma_f32_16x16x32_bf16 v[152:155], v[90:93], v[176:179], v[152:155]
	s_nop 6
	v_cvt_pk_bf16_f32 v188, v148, v149
	v_cvt_pk_bf16_f32 v189, v150, v151
	v_cvt_pk_bf16_f32 v190, v152, v153
	v_cvt_pk_bf16_f32 v191, v154, v155
	ds_write_b64 v209, v[188:189]
	ds_write_b64 v209, v[190:191] offset:4352
	s_add_i32 s22, s22, 1
	s_waitcnt lgkmcnt(0)
	s_barrier
; __device__ void dn_scan_block(const Params& p, int L, int item) {
;     ...
;   DN_LOAD(A, 0); DN_LOAD(B, 1);
;   __syncthreads();
;   for (int n = 0; n < 63; n += 3) {
;     DN_LOAD(C, n + 2); DN_STEP(A, n);
;     DN_LOAD(A, n + 3); DN_STEP(B, n + 1);
;     if (n + 4 < 64) DN_LOAD(B, n + 4);
;     DN_STEP(C, n + 2);
;   }
;   DN_STEP(A, 63);
	s_add_i32 s0, s22, 3
	s_min_u32 s0, s0, 63
	s_add_i32 s1, s42, s0
	s_lshl_b32 s2, s0, 2
	s_add_u32 s14, s36, s2
	s_addc_u32 s15, s37, 0
	s_add_i32 s2, s1, 0xfffff8e4
	s_cmpk_lt_i32 s1, 0x71c
	s_cselect_b32 s1, s1, s2
	s_cselect_b32 s2, s8, s16
	s_cselect_b32 s3, s9, s17
	s_mul_hi_u32 s13, s1, 0x12000
	s_mul_i32 s12, s1, 0x12000
	s_add_u32 s12, s2, s12
	s_addc_u32 s13, s3, s13
	global_load_dwordx2 v[94:95], v198, s[12:13]
	global_load_dwordx2 v[96:97], v198, s[12:13] offset:512
	global_load_dword v102, v1, s[14:15]
	global_load_dwordx4 v[70:73], v196, s[12:13]
	global_load_dwordx4 v[74:77], v196, s[12:13] offset:1024
	global_load_dwordx4 v[78:81], v196, s[12:13] offset:2048
	global_load_dwordx4 v[82:85], v196, s[12:13] offset:3072
	global_load_dwordx4 v[86:89], v197, s[12:13]
	global_load_dwordx4 v[90:93], v197, s[12:13] offset:1024
	ds_read_b128 v[156:159], v206 offset:0
	ds_read_b128 v[172:175], v206 offset:4352
	ds_read_b128 v[160:163], v206 offset:64
	ds_read_b128 v[176:179], v206 offset:4416
	ds_read_b128 v[164:167], v206 offset:128
	ds_read_b128 v[180:183], v206 offset:4480
	ds_read_b128 v[168:171], v206 offset:192
	ds_read_b128 v[184:187], v206 offset:4544
	s_waitcnt vmcnt(27)
	v_lshlrev_b32_e32 v140, 16, v128
	v_and_b32_e32 v141, 0xffff0000, v128
	v_lshlrev_b32_e32 v142, 16, v129
	v_and_b32_e32 v143, 0xffff0000, v129
	v_lshlrev_b32_e32 v144, 16, v130
	v_and_b32_e32 v145, 0xffff0000, v130
	v_lshlrev_b32_e32 v146, 16, v131
	v_and_b32_e32 v147, 0xffff0000, v131
	v_pk_mul_f32 v[148:149], v[136:137], v[148:149] op_sel_hi:[0,1]
	v_pk_mul_f32 v[150:151], v[136:137], v[150:151] op_sel_hi:[0,1]
	v_pk_mul_f32 v[152:153], v[136:137], v[152:153] op_sel_hi:[0,1]
	v_pk_mul_f32 v[154:155], v[136:137], v[154:155] op_sel_hi:[0,1]
	s_waitcnt lgkmcnt(7)
	v_mfma_f32_16x16x32_bf16 v[140:143], v[104:107], v[156:159], v[140:143]
	s_waitcnt lgkmcnt(6)
	v_mfma_f32_16x16x32_bf16 v[144:147], v[104:107], v[172:175], v[144:147]
	s_waitcnt lgkmcnt(5)
	v_mfma_f32_16x16x32_bf16 v[140:143], v[108:111], v[160:163], v[140:143]
	s_waitcnt lgkmcnt(4)
	v_mfma_f32_16x16x32_bf16 v[144:147], v[108:111], v[176:179], v[144:147]
	s_waitcnt lgkmcnt(3)
	v_mfma_f32_16x16x32_bf16 v[140:143], v[112:115], v[164:167], v[140:143]
	s_waitcnt lgkmcnt(2)
	v_mfma_f32_16x16x32_bf16 v[144:147], v[112:115], v[180:183], v[144:147]
	s_waitcnt lgkmcnt(1)
	v_mfma_f32_16x16x32_bf16 v[140:143], v[116:119], v[168:171], v[140:143]
	s_waitcnt lgkmcnt(0)
	v_mfma_f32_16x16x32_bf16 v[144:147], v[116:119], v[184:187], v[144:147]
	s_nop 6
	v_cvt_pk_bf16_f32 v188, v140, v141
	v_cvt_pk_bf16_f32 v189, v142, v143
	v_cvt_pk_bf16_f32 v190, v144, v145
	v_cvt_pk_bf16_f32 v191, v146, v147
	ds_write_b64 v207, v[188:189]
	ds_write_b64 v207, v[190:191] offset:2304
	s_waitcnt lgkmcnt(0)
	s_barrier
	ds_read_b128 v[156:159], v208 offset:8704
	ds_read_b128 v[172:175], v208 offset:11008
	ds_read_b128 v[160:163], v208 offset:8768
	ds_read_b128 v[176:179], v208 offset:11072
	s_waitcnt lgkmcnt(3)
	v_mfma_f32_16x16x32_bf16 v[148:151], v[120:123], v[156:159], v[148:151]
	s_waitcnt lgkmcnt(2)
	v_mfma_f32_16x16x32_bf16 v[152:155], v[120:123], v[172:175], v[152:155]
	s_waitcnt lgkmcnt(1)
	v_mfma_f32_16x16x32_bf16 v[148:151], v[124:127], v[160:163], v[148:151]
	s_waitcnt lgkmcnt(0)
	v_mfma_f32_16x16x32_bf16 v[152:155], v[124:127], v[176:179], v[152:155]
	s_nop 6
	v_cvt_pk_bf16_f32 v188, v148, v149
	v_cvt_pk_bf16_f32 v189, v150, v151
	v_cvt_pk_bf16_f32 v190, v152, v153
	v_cvt_pk_bf16_f32 v191, v154, v155
	ds_write_b64 v209, v[188:189]
	ds_write_b64 v209, v[190:191] offset:4352
	s_add_i32 s22, s22, 1
	s_waitcnt lgkmcnt(0)
	s_barrier
	s_cmp_lt_u32 s22, 64
	s_cbranch_scc1 .Ldn_scan_loop_u
	s_branch .LBB0_259
.Ldn_scan_o:
	s_mov_b32 s0, 0
	s_add_i32 s1, s42, s0
	s_lshl_b32 s2, s0, 2
	s_add_u32 s14, s36, s2
	s_addc_u32 s15, s37, 0
	s_add_i32 s2, s1, 0xfffff8e4
	s_cmpk_lt_i32 s1, 0x71c
	s_cselect_b32 s1, s1, s2
	s_cselect_b32 s2, s8, s16
	s_cselect_b32 s3, s9, s17
	s_mul_hi_u32 s13, s1, 0x12000
	s_mul_i32 s12, s1, 0x12000
	s_add_u32 s12, s2, s12
	s_addc_u32 s13, s3, s13
	global_load_dword v34, v1, s[14:15]
	global_load_dwordx4 v[2:5], v196, s[12:13]
	global_load_dwordx4 v[6:9], v196, s[12:13] offset:1024
	global_load_dwordx4 v[10:13], v196, s[12:13] offset:2048
	global_load_dwordx4 v[14:17], v196, s[12:13] offset:3072
	global_load_dwordx4 v[26:29], v198, s[12:13]
	global_load_dwordx4 v[30:33], v198, s[12:13] offset:1024
	global_load_dwordx4 v[18:21], v197, s[12:13]
	global_load_dwordx4 v[22:25], v197, s[12:13] offset:1024
	global_load_dword v210, v1, s[14:15]
	global_load_dword v210, v1, s[14:15]
	global_load_dword v210, v1, s[14:15]
	global_load_dword v210, v1, s[14:15]
	global_load_dword v210, v1, s[14:15]
	global_load_dword v210, v1, s[14:15]
	global_load_dword v210, v1, s[14:15]
	global_load_dword v210, v1, s[14:15]
	s_mov_b32 s0, 1
	s_add_i32 s1, s42, s0
	s_lshl_b32 s2, s0, 2
	s_add_u32 s14, s36, s2
	s_addc_u32 s15, s37, 0
	s_add_i32 s2, s1, 0xfffff8e4
	s_cmpk_lt_i32 s1, 0x71c
	s_cselect_b32 s1, s1, s2
	s_cselect_b32 s2, s8, s16
	s_cselect_b32 s3, s9, s17
	s_mul_hi_u32 s13, s1, 0x12000
	s_mul_i32 s12, s1, 0x12000
	s_add_u32 s12, s2, s12
	s_addc_u32 s13, s3, s13
	global_load_dword v68, v1, s[14:15]
	global_load_dwordx4 v[36:39], v196, s[12:13]
	global_load_dwordx4 v[40:43], v196, s[12:13] offset:1024
	global_load_dwordx4 v[44:47], v196, s[12:13] offset:2048
	global_load_dwordx4 v[48:51], v196, s[12:13] offset:3072
	global_load_dwordx4 v[60:63], v198, s[12:13]
	global_load_dwordx4 v[64:67], v198, s[12:13] offset:1024
	global_load_dwordx4 v[52:55], v197, s[12:13]
	global_load_dwordx4 v[56:59], v197, s[12:13] offset:1024
; __device__ void dn_scan_block(const Params& p, int L, int item) {
;     ...
;   DN_LOAD(A, 0); DN_LOAD(B, 1);
;   __syncthreads();
;   for (int n = 0; n < 63; n += 3) {
;     DN_LOAD(C, n + 2); DN_STEP(A, n);
;     DN_LOAD(A, n + 3); DN_STEP(B, n + 1);
;     if (n + 4 < 64) DN_LOAD(B, n + 4);
;     DN_STEP(C, n + 2);
;   }
;   DN_STEP(A, 63);
	global_load_dword v210, v1, s[14:15]
	global_load_dword v210, v1, s[14:15]
	global_load_dword v210, v1, s[14:15]
	global_load_dword v210, v1, s[14:15]
	global_load_dword v210, v1, s[14:15]
	global_load_dword v210, v1, s[14:15]
	global_load_dword v210, v1, s[14:15]
	global_load_dword v210, v1, s[14:15]
	s_mov_b32 s0, 2
	s_add_i32 s1, s42, s0
	s_lshl_b32 s2, s0, 2
	s_add_u32 s14, s36, s2
	s_addc_u32 s15, s37, 0
	s_add_i32 s2, s1, 0xfffff8e4
	s_cmpk_lt_i32 s1, 0x71c
	s_cselect_b32 s1, s1, s2
	s_cselect_b32 s2, s8, s16
	s_cselect_b32 s3, s9, s17
	s_mul_hi_u32 s13, s1, 0x12000
	s_mul_i32 s12, s1, 0x12000
	s_add_u32 s12, s2, s12
	s_addc_u32 s13, s3, s13
	global_load_dword v102, v1, s[14:15]
	global_load_dwordx4 v[70:73], v196, s[12:13]
	global_load_dwordx4 v[74:77], v196, s[12:13] offset:1024
	global_load_dwordx4 v[78:81], v196, s[12:13] offset:2048
	global_load_dwordx4 v[82:85], v196, s[12:13] offset:3072
	global_load_dwordx4 v[94:97], v198, s[12:13]
	global_load_dwordx4 v[98:101], v198, s[12:13] offset:1024
	global_load_dwordx4 v[86:89], v197, s[12:13]
	global_load_dwordx4 v[90:93], v197, s[12:13] offset:1024
	global_load_dword v210, v1, s[14:15]
	global_load_dword v210, v1, s[14:15]
	global_load_dword v210, v1, s[14:15]
	global_load_dword v210, v1, s[14:15]
	global_load_dword v210, v1, s[14:15]
	global_load_dword v210, v1, s[14:15]
	global_load_dword v210, v1, s[14:15]
	global_load_dword v210, v1, s[14:15]
	s_waitcnt lgkmcnt(0)
	s_barrier
.Ldn_scan_loop_o:
	s_add_i32 s0, s22, 3
	s_min_u32 s0, s0, 63
	s_add_i32 s1, s42, s0
	s_lshl_b32 s2, s0, 2
	s_add_u32 s14, s36, s2
	s_addc_u32 s15, s37, 0
	s_add_i32 s2, s1, 0xfffff8e4
	s_cmpk_lt_i32 s1, 0x71c
	s_cselect_b32 s1, s1, s2
	s_cselect_b32 s2, s8, s16
	s_cselect_b32 s3, s9, s17
	s_mul_hi_u32 s13, s1, 0x12000
	s_mul_i32 s12, s1, 0x12000
	s_add_u32 s12, s2, s12
	s_addc_u32 s13, s3, s13
	global_load_dword v136, v1, s[14:15]
	global_load_dwordx4 v[104:107], v196, s[12:13]
	global_load_dwordx4 v[108:111], v196, s[12:13] offset:1024
	global_load_dwordx4 v[112:115], v196, s[12:13] offset:2048
	global_load_dwordx4 v[116:119], v196, s[12:13] offset:3072
	global_load_dwordx4 v[128:131], v198, s[12:13]
	global_load_dwordx4 v[132:135], v198, s[12:13] offset:1024
	global_load_dwordx4 v[120:123], v197, s[12:13]
	global_load_dwordx4 v[124:127], v197, s[12:13] offset:1024
	ds_read_b128 v[156:159], v206 offset:0
	ds_read_b128 v[172:175], v206 offset:4352
	ds_read_b128 v[160:163], v206 offset:64
	ds_read_b128 v[176:179], v206 offset:4416
	ds_read_b128 v[164:167], v206 offset:128
	ds_read_b128 v[180:183], v206 offset:4480
	ds_read_b128 v[168:171], v206 offset:192
	ds_read_b128 v[184:187], v206 offset:4544
	s_waitcnt vmcnt(51)
	v_pk_mul_f32 v[148:149], v[34:35], v[148:149] op_sel_hi:[0,1]
	v_pk_mul_f32 v[150:151], v[34:35], v[150:151] op_sel_hi:[0,1]
	v_pk_mul_f32 v[152:153], v[34:35], v[152:153] op_sel_hi:[0,1]
	v_pk_mul_f32 v[154:155], v[34:35], v[154:155] op_sel_hi:[0,1]
	s_waitcnt lgkmcnt(7)
	v_mfma_f32_16x16x32_bf16 v[140:143], v[2:5], v[156:159], 0
	s_waitcnt lgkmcnt(6)
	v_mfma_f32_16x16x32_bf16 v[144:147], v[2:5], v[172:175], 0
	s_waitcnt lgkmcnt(5)
	v_mfma_f32_16x16x32_bf16 v[140:143], v[6:9], v[160:163], v[140:143]
	s_waitcnt lgkmcnt(4)
	v_mfma_f32_16x16x32_bf16 v[144:147], v[6:9], v[176:179], v[144:147]
	s_waitcnt lgkmcnt(3)
	v_mfma_f32_16x16x32_bf16 v[140:143], v[10:13], v[164:167], v[140:143]
	s_waitcnt lgkmcnt(2)
	v_mfma_f32_16x16x32_bf16 v[144:147], v[10:13], v[180:183], v[144:147]
	s_waitcnt lgkmcnt(1)
	v_mfma_f32_16x16x32_bf16 v[140:143], v[14:17], v[168:171], v[140:143]
	s_waitcnt lgkmcnt(0)
	v_mfma_f32_16x16x32_bf16 v[144:147], v[14:17], v[184:187], v[144:147]
	s_waitcnt lgkmcnt(0)
	s_barrier
	ds_read_b128 v[156:159], v208 offset:8704
	ds_read_b128 v[172:175], v208 offset:11008
	ds_read_b128 v[160:163], v208 offset:8768
	ds_read_b128 v[176:179], v208 offset:11072
	s_waitcnt lgkmcnt(3)
	v_mfma_f32_16x16x32_bf16 v[148:151], v[18:21], v[156:159], v[148:151]
	s_waitcnt lgkmcnt(2)
	v_mfma_f32_16x16x32_bf16 v[152:155], v[18:21], v[172:175], v[152:155]
	s_waitcnt lgkmcnt(1)
	v_mfma_f32_16x16x32_bf16 v[148:151], v[22:25], v[160:163], v[148:151]
	s_waitcnt lgkmcnt(0)
	v_mfma_f32_16x16x32_bf16 v[152:155], v[22:25], v[176:179], v[152:155]
	v_mfma_f32_16x16x32_bf16 v[140:143], v[26:29], v[156:159], v[140:143]
	v_mfma_f32_16x16x32_bf16 v[144:147], v[26:29], v[172:175], v[144:147]
	v_mfma_f32_16x16x32_bf16 v[140:143], v[30:33], v[160:163], v[140:143]
	v_mfma_f32_16x16x32_bf16 v[144:147], v[30:33], v[176:179], v[144:147]
	s_nop 2
	v_cvt_pk_bf16_f32 v188, v148, v149
	v_cvt_pk_bf16_f32 v189, v150, v151
	v_cvt_pk_bf16_f32 v190, v152, v153
	v_cvt_pk_bf16_f32 v191, v154, v155
	ds_write_b64 v209, v[188:189]
	ds_write_b64 v209, v[190:191] offset:4352
	v_cvt_pk_bf16_f32 v192, v140, v141
	v_cvt_pk_bf16_f32 v193, v142, v143
	v_cvt_pk_bf16_f32 v194, v144, v145
	v_cvt_pk_bf16_f32 v195, v146, v147
	global_store_short v202, v192, s[18:19]
	global_store_short_d16_hi v203, v192, s[18:19]
	global_store_short v204, v193, s[18:19]
	global_store_short_d16_hi v205, v193, s[18:19]
	global_store_short v202, v194, s[18:19] offset:32
	global_store_short_d16_hi v203, v194, s[18:19] offset:32
	global_store_short v204, v195, s[18:19] offset:32
	global_store_short_d16_hi v205, v195, s[18:19] offset:32
	s_add_u32 s18, s18, 0x70000
	s_addc_u32 s19, s19, 0
	s_add_i32 s22, s22, 1
	s_waitcnt lgkmcnt(0)
	s_barrier
; __device__ void dn_scan_block(const Params& p, int L, int item) {
;     ...
;   DN_LOAD(A, 0); DN_LOAD(B, 1);
;   __syncthreads();
;   for (int n = 0; n < 63; n += 3) {
;     DN_LOAD(C, n + 2); DN_STEP(A, n);
;     DN_LOAD(A, n + 3); DN_STEP(B, n + 1);
;     if (n + 4 < 64) DN_LOAD(B, n + 4);
;     DN_STEP(C, n + 2);
;   }
;   DN_STEP(A, 63);
	s_add_i32 s0, s22, 3
	s_min_u32 s0, s0, 63
	s_add_i32 s1, s42, s0
	s_lshl_b32 s2, s0, 2
	s_add_u32 s14, s36, s2
	s_addc_u32 s15, s37, 0
	s_add_i32 s2, s1, 0xfffff8e4
	s_cmpk_lt_i32 s1, 0x71c
	s_cselect_b32 s1, s1, s2
	s_cselect_b32 s2, s8, s16
	s_cselect_b32 s3, s9, s17
	s_mul_hi_u32 s13, s1, 0x12000
	s_mul_i32 s12, s1, 0x12000
	s_add_u32 s12, s2, s12
	s_addc_u32 s13, s3, s13
	global_load_dword v34, v1, s[14:15]
	global_load_dwordx4 v[2:5], v196, s[12:13]
	global_load_dwordx4 v[6:9], v196, s[12:13] offset:1024
	global_load_dwordx4 v[10:13], v196, s[12:13] offset:2048
	global_load_dwordx4 v[14:17], v196, s[12:13] offset:3072
	global_load_dwordx4 v[26:29], v198, s[12:13]
	global_load_dwordx4 v[30:33], v198, s[12:13] offset:1024
	global_load_dwordx4 v[18:21], v197, s[12:13]
	global_load_dwordx4 v[22:25], v197, s[12:13] offset:1024
	ds_read_b128 v[156:159], v206 offset:0
	ds_read_b128 v[172:175], v206 offset:4352
	ds_read_b128 v[160:163], v206 offset:64
	ds_read_b128 v[176:179], v206 offset:4416
	ds_read_b128 v[164:167], v206 offset:128
	ds_read_b128 v[180:183], v206 offset:4480
	ds_read_b128 v[168:171], v206 offset:192
	ds_read_b128 v[184:187], v206 offset:4544
	s_waitcnt vmcnt(51)
	v_pk_mul_f32 v[148:149], v[68:69], v[148:149] op_sel_hi:[0,1]
	v_pk_mul_f32 v[150:151], v[68:69], v[150:151] op_sel_hi:[0,1]
	v_pk_mul_f32 v[152:153], v[68:69], v[152:153] op_sel_hi:[0,1]
	v_pk_mul_f32 v[154:155], v[68:69], v[154:155] op_sel_hi:[0,1]
	s_waitcnt lgkmcnt(7)
	v_mfma_f32_16x16x32_bf16 v[140:143], v[36:39], v[156:159], 0
	s_waitcnt lgkmcnt(6)
	v_mfma_f32_16x16x32_bf16 v[144:147], v[36:39], v[172:175], 0
	s_waitcnt lgkmcnt(5)
	v_mfma_f32_16x16x32_bf16 v[140:143], v[40:43], v[160:163], v[140:143]
	s_waitcnt lgkmcnt(4)
	v_mfma_f32_16x16x32_bf16 v[144:147], v[40:43], v[176:179], v[144:147]
	s_waitcnt lgkmcnt(3)
	v_mfma_f32_16x16x32_bf16 v[140:143], v[44:47], v[164:167], v[140:143]
	s_waitcnt lgkmcnt(2)
	v_mfma_f32_16x16x32_bf16 v[144:147], v[44:47], v[180:183], v[144:147]
	s_waitcnt lgkmcnt(1)
	v_mfma_f32_16x16x32_bf16 v[140:143], v[48:51], v[168:171], v[140:143]
	s_waitcnt lgkmcnt(0)
	v_mfma_f32_16x16x32_bf16 v[144:147], v[48:51], v[184:187], v[144:147]
	s_waitcnt lgkmcnt(0)
	s_barrier
	ds_read_b128 v[156:159], v208 offset:8704
	ds_read_b128 v[172:175], v208 offset:11008
	ds_read_b128 v[160:163], v208 offset:8768
	ds_read_b128 v[176:179], v208 offset:11072
	s_waitcnt lgkmcnt(3)
	v_mfma_f32_16x16x32_bf16 v[148:151], v[52:55], v[156:159], v[148:151]
	s_waitcnt lgkmcnt(2)
	v_mfma_f32_16x16x32_bf16 v[152:155], v[52:55], v[172:175], v[152:155]
	s_waitcnt lgkmcnt(1)
	v_mfma_f32_16x16x32_bf16 v[148:151], v[56:59], v[160:163], v[148:151]
	s_waitcnt lgkmcnt(0)
	v_mfma_f32_16x16x32_bf16 v[152:155], v[56:59], v[176:179], v[152:155]
	v_mfma_f32_16x16x32_bf16 v[140:143], v[60:63], v[156:159], v[140:143]
	v_mfma_f32_16x16x32_bf16 v[144:147], v[60:63], v[172:175], v[144:147]
	v_mfma_f32_16x16x32_bf16 v[140:143], v[64:67], v[160:163], v[140:143]
	v_mfma_f32_16x16x32_bf16 v[144:147], v[64:67], v[176:179], v[144:147]
	s_nop 2
	v_cvt_pk_bf16_f32 v188, v148, v149
	v_cvt_pk_bf16_f32 v189, v150, v151
	v_cvt_pk_bf16_f32 v190, v152, v153
	v_cvt_pk_bf16_f32 v191, v154, v155
	ds_write_b64 v209, v[188:189]
	ds_write_b64 v209, v[190:191] offset:4352
	v_cvt_pk_bf16_f32 v192, v140, v141
	v_cvt_pk_bf16_f32 v193, v142, v143
	v_cvt_pk_bf16_f32 v194, v144, v145
	v_cvt_pk_bf16_f32 v195, v146, v147
	global_store_short v202, v192, s[18:19]
	global_store_short_d16_hi v203, v192, s[18:19]
	global_store_short v204, v193, s[18:19]
	global_store_short_d16_hi v205, v193, s[18:19]
	global_store_short v202, v194, s[18:19] offset:32
	global_store_short_d16_hi v203, v194, s[18:19] offset:32
	global_store_short v204, v195, s[18:19] offset:32
	global_store_short_d16_hi v205, v195, s[18:19] offset:32
	s_add_u32 s18, s18, 0x70000
	s_addc_u32 s19, s19, 0
	s_add_i32 s22, s22, 1
	s_waitcnt lgkmcnt(0)
	s_barrier
	s_add_i32 s0, s22, 3
	s_min_u32 s0, s0, 63
	s_add_i32 s1, s42, s0
	s_lshl_b32 s2, s0, 2
	s_add_u32 s14, s36, s2
	s_addc_u32 s15, s37, 0
	s_add_i32 s2, s1, 0xfffff8e4
	s_cmpk_lt_i32 s1, 0x71c
	s_cselect_b32 s1, s1, s2
	s_cselect_b32 s2, s8, s16
	s_cselect_b32 s3, s9, s17
	s_mul_hi_u32 s13, s1, 0x12000
	s_mul_i32 s12, s1, 0x12000
	s_add_u32 s12, s2, s12
	s_addc_u32 s13, s3, s13
	global_load_dword v68, v1, s[14:15]
	global_load_dwordx4 v[36:39], v196, s[12:13]
	global_load_dwordx4 v[40:43], v196, s[12:13] offset:1024
	global_load_dwordx4 v[44:47], v196, s[12:13] offset:2048
	global_load_dwordx4 v[48:51], v196, s[12:13] offset:3072
	global_load_dwordx4 v[60:63], v198, s[12:13]
	global_load_dwordx4 v[64:67], v198, s[12:13] offset:1024
	global_load_dwordx4 v[52:55], v197, s[12:13]
	global_load_dwordx4 v[56:59], v197, s[12:13] offset:1024
	ds_read_b128 v[156:159], v206 offset:0
	ds_read_b128 v[172:175], v206 offset:4352
	ds_read_b128 v[160:163], v206 offset:64
	ds_read_b128 v[176:179], v206 offset:4416
	ds_read_b128 v[164:167], v206 offset:128
	ds_read_b128 v[180:183], v206 offset:4480
	ds_read_b128 v[168:171], v206 offset:192
	ds_read_b128 v[184:187], v206 offset:4544
	s_waitcnt vmcnt(51)
	v_pk_mul_f32 v[148:149], v[102:103], v[148:149] op_sel_hi:[0,1]
	v_pk_mul_f32 v[150:151], v[102:103], v[150:151] op_sel_hi:[0,1]
	v_pk_mul_f32 v[152:153], v[102:103], v[152:153] op_sel_hi:[0,1]
	v_pk_mul_f32 v[154:155], v[102:103], v[154:155] op_sel_hi:[0,1]
	s_waitcnt lgkmcnt(7)
	v_mfma_f32_16x16x32_bf16 v[140:143], v[70:73], v[156:159], 0
	s_waitcnt lgkmcnt(6)
	v_mfma_f32_16x16x32_bf16 v[144:147], v[70:73], v[172:175], 0
	s_waitcnt lgkmcnt(5)
	v_mfma_f32_16x16x32_bf16 v[140:143], v[74:77], v[160:163], v[140:143]
	s_waitcnt lgkmcnt(4)
	v_mfma_f32_16x16x32_bf16 v[144:147], v[74:77], v[176:179], v[144:147]
	s_waitcnt lgkmcnt(3)
	v_mfma_f32_16x16x32_bf16 v[140:143], v[78:81], v[164:167], v[140:143]
	s_waitcnt lgkmcnt(2)
	v_mfma_f32_16x16x32_bf16 v[144:147], v[78:81], v[180:183], v[144:147]
	s_waitcnt lgkmcnt(1)
	v_mfma_f32_16x16x32_bf16 v[140:143], v[82:85], v[168:171], v[140:143]
	s_waitcnt lgkmcnt(0)
	v_mfma_f32_16x16x32_bf16 v[144:147], v[82:85], v[184:187], v[144:147]
	s_waitcnt lgkmcnt(0)
	s_barrier
; __device__ void dn_scan_block(const Params& p, int L, int item) {
;     ...
;   DN_LOAD(A, 0); DN_LOAD(B, 1);
;   __syncthreads();
;   for (int n = 0; n < 63; n += 3) {
;     DN_LOAD(C, n + 2); DN_STEP(A, n);
;     DN_LOAD(A, n + 3); DN_STEP(B, n + 1);
;     if (n + 4 < 64) DN_LOAD(B, n + 4);
;     DN_STEP(C, n + 2);
;   }
;   DN_STEP(A, 63);
	ds_read_b128 v[156:159], v208 offset:8704
	ds_read_b128 v[172:175], v208 offset:11008
	ds_read_b128 v[160:163], v208 offset:8768
	ds_read_b128 v[176:179], v208 offset:11072
	s_waitcnt lgkmcnt(3)
	v_mfma_f32_16x16x32_bf16 v[148:151], v[86:89], v[156:159], v[148:151]
	s_waitcnt lgkmcnt(2)
	v_mfma_f32_16x16x32_bf16 v[152:155], v[86:89], v[172:175], v[152:155]
	s_waitcnt lgkmcnt(1)
	v_mfma_f32_16x16x32_bf16 v[148:151], v[90:93], v[160:163], v[148:151]
	s_waitcnt lgkmcnt(0)
	v_mfma_f32_16x16x32_bf16 v[152:155], v[90:93], v[176:179], v[152:155]
	v_mfma_f32_16x16x32_bf16 v[140:143], v[94:97], v[156:159], v[140:143]
	v_mfma_f32_16x16x32_bf16 v[144:147], v[94:97], v[172:175], v[144:147]
	v_mfma_f32_16x16x32_bf16 v[140:143], v[98:101], v[160:163], v[140:143]
	v_mfma_f32_16x16x32_bf16 v[144:147], v[98:101], v[176:179], v[144:147]
	s_nop 2
	v_cvt_pk_bf16_f32 v188, v148, v149
	v_cvt_pk_bf16_f32 v189, v150, v151
	v_cvt_pk_bf16_f32 v190, v152, v153
	v_cvt_pk_bf16_f32 v191, v154, v155
	ds_write_b64 v209, v[188:189]
	ds_write_b64 v209, v[190:191] offset:4352
	v_cvt_pk_bf16_f32 v192, v140, v141
	v_cvt_pk_bf16_f32 v193, v142, v143
	v_cvt_pk_bf16_f32 v194, v144, v145
	v_cvt_pk_bf16_f32 v195, v146, v147
	global_store_short v202, v192, s[18:19]
	global_store_short_d16_hi v203, v192, s[18:19]
	global_store_short v204, v193, s[18:19]
	global_store_short_d16_hi v205, v193, s[18:19]
	global_store_short v202, v194, s[18:19] offset:32
	global_store_short_d16_hi v203, v194, s[18:19] offset:32
	global_store_short v204, v195, s[18:19] offset:32
	global_store_short_d16_hi v205, v195, s[18:19] offset:32
	s_add_u32 s18, s18, 0x70000
	s_addc_u32 s19, s19, 0
	s_add_i32 s22, s22, 1
	s_waitcnt lgkmcnt(0)
	s_barrier
	s_add_i32 s0, s22, 3
	s_min_u32 s0, s0, 63
	s_add_i32 s1, s42, s0
	s_lshl_b32 s2, s0, 2
	s_add_u32 s14, s36, s2
	s_addc_u32 s15, s37, 0
	s_add_i32 s2, s1, 0xfffff8e4
	s_cmpk_lt_i32 s1, 0x71c
	s_cselect_b32 s1, s1, s2
	s_cselect_b32 s2, s8, s16
	s_cselect_b32 s3, s9, s17
	s_mul_hi_u32 s13, s1, 0x12000
	s_mul_i32 s12, s1, 0x12000
	s_add_u32 s12, s2, s12
	s_addc_u32 s13, s3, s13
	global_load_dword v102, v1, s[14:15]
	global_load_dwordx4 v[70:73], v196, s[12:13]
	global_load_dwordx4 v[74:77], v196, s[12:13] offset:1024
	global_load_dwordx4 v[78:81], v196, s[12:13] offset:2048
	global_load_dwordx4 v[82:85], v196, s[12:13] offset:3072
	global_load_dwordx4 v[94:97], v198, s[12:13]
	global_load_dwordx4 v[98:101], v198, s[12:13] offset:1024
	global_load_dwordx4 v[86:89], v197, s[12:13]
	global_load_dwordx4 v[90:93], v197, s[12:13] offset:1024
	ds_read_b128 v[156:159], v206 offset:0
	ds_read_b128 v[172:175], v206 offset:4352
	ds_read_b128 v[160:163], v206 offset:64
	ds_read_b128 v[176:179], v206 offset:4416
	ds_read_b128 v[164:167], v206 offset:128
	ds_read_b128 v[180:183], v206 offset:4480
	ds_read_b128 v[168:171], v206 offset:192
	ds_read_b128 v[184:187], v206 offset:4544
	s_waitcnt vmcnt(51)
	v_pk_mul_f32 v[148:149], v[136:137], v[148:149] op_sel_hi:[0,1]
	v_pk_mul_f32 v[150:151], v[136:137], v[150:151] op_sel_hi:[0,1]
	v_pk_mul_f32 v[152:153], v[136:137], v[152:153] op_sel_hi:[0,1]
	v_pk_mul_f32 v[154:155], v[136:137], v[154:155] op_sel_hi:[0,1]
	s_waitcnt lgkmcnt(7)
	v_mfma_f32_16x16x32_bf16 v[140:143], v[104:107], v[156:159], 0
	s_waitcnt lgkmcnt(6)
	v_mfma_f32_16x16x32_bf16 v[144:147], v[104:107], v[172:175], 0
	s_waitcnt lgkmcnt(5)
	v_mfma_f32_16x16x32_bf16 v[140:143], v[108:111], v[160:163], v[140:143]
	s_waitcnt lgkmcnt(4)
	v_mfma_f32_16x16x32_bf16 v[144:147], v[108:111], v[176:179], v[144:147]
	s_waitcnt lgkmcnt(3)
	v_mfma_f32_16x16x32_bf16 v[140:143], v[112:115], v[164:167], v[140:143]
	s_waitcnt lgkmcnt(2)
	v_mfma_f32_16x16x32_bf16 v[144:147], v[112:115], v[180:183], v[144:147]
	s_waitcnt lgkmcnt(1)
	v_mfma_f32_16x16x32_bf16 v[140:143], v[116:119], v[168:171], v[140:143]
	s_waitcnt lgkmcnt(0)
	v_mfma_f32_16x16x32_bf16 v[144:147], v[116:119], v[184:187], v[144:147]
	s_waitcnt lgkmcnt(0)
	s_barrier
	ds_read_b128 v[156:159], v208 offset:8704
	ds_read_b128 v[172:175], v208 offset:11008
	ds_read_b128 v[160:163], v208 offset:8768
	ds_read_b128 v[176:179], v208 offset:11072
	s_waitcnt lgkmcnt(3)
	v_mfma_f32_16x16x32_bf16 v[148:151], v[120:123], v[156:159], v[148:151]
	s_waitcnt lgkmcnt(2)
	v_mfma_f32_16x16x32_bf16 v[152:155], v[120:123], v[172:175], v[152:155]
	s_waitcnt lgkmcnt(1)
	v_mfma_f32_16x16x32_bf16 v[148:151], v[124:127], v[160:163], v[148:151]
	s_waitcnt lgkmcnt(0)
	v_mfma_f32_16x16x32_bf16 v[152:155], v[124:127], v[176:179], v[152:155]
	v_mfma_f32_16x16x32_bf16 v[140:143], v[128:131], v[156:159], v[140:143]
	v_mfma_f32_16x16x32_bf16 v[144:147], v[128:131], v[172:175], v[144:147]
	v_mfma_f32_16x16x32_bf16 v[140:143], v[132:135], v[160:163], v[140:143]
	v_mfma_f32_16x16x32_bf16 v[144:147], v[132:135], v[176:179], v[144:147]
	s_nop 2
	v_cvt_pk_bf16_f32 v188, v148, v149
	v_cvt_pk_bf16_f32 v189, v150, v151
	v_cvt_pk_bf16_f32 v190, v152, v153
	v_cvt_pk_bf16_f32 v191, v154, v155
	ds_write_b64 v209, v[188:189]
	ds_write_b64 v209, v[190:191] offset:4352
	v_cvt_pk_bf16_f32 v192, v140, v141
	v_cvt_pk_bf16_f32 v193, v142, v143
	v_cvt_pk_bf16_f32 v194, v144, v145
	v_cvt_pk_bf16_f32 v195, v146, v147
	global_store_short v202, v192, s[18:19]
	global_store_short_d16_hi v203, v192, s[18:19]
	global_store_short v204, v193, s[18:19]
	global_store_short_d16_hi v205, v193, s[18:19]
	global_store_short v202, v194, s[18:19] offset:32
	global_store_short_d16_hi v203, v194, s[18:19] offset:32
	global_store_short v204, v195, s[18:19] offset:32
	global_store_short_d16_hi v205, v195, s[18:19] offset:32
	s_add_u32 s18, s18, 0x70000
	s_addc_u32 s19, s19, 0
	s_add_i32 s22, s22, 1
	s_waitcnt lgkmcnt(0)
	s_barrier
	s_cmp_lt_u32 s22, 64
	s_cbranch_scc1 .Ldn_scan_loop_o
	s_branch .LBB0_259
